# norm-phase reductions fully LDS-free (permlane32/16 swaps + DPP) on top of rsq dead-path removal
# baseline (speedup 1.0000x reference)
.LBB0_99:
	s_or_b64 exec, exec, s[8:9]
	s_waitcnt vmcnt(7)
	v_mov_b32_e32 v50, v37
	s_waitcnt vmcnt(6)
	v_mov_b32_e32 v51, v33
	v_mov_b32_e32 v48, v36
	v_mov_b32_e32 v49, v32
	v_pk_mul_f32 v[50:51], v[50:51], v[50:51]
	s_waitcnt vmcnt(5)
	v_mov_b32_e32 v52, v29
	v_pk_fma_f32 v[48:49], v[48:49], v[48:49], v[50:51]
	v_mov_b32_e32 v50, v38
	v_mov_b32_e32 v51, v34
	v_pk_fma_f32 v[48:49], v[50:51], v[50:51], v[48:49]
	v_mov_b32_e32 v50, v39
	v_mov_b32_e32 v51, v35
	s_waitcnt vmcnt(4)
	v_mov_b32_e32 v53, v25
	v_pk_fma_f32 v[48:49], v[50:51], v[50:51], v[48:49]
	v_mov_b32_e32 v50, v28
	v_mov_b32_e32 v51, v24
	v_pk_mul_f32 v[52:53], v[52:53], v[52:53]
	v_add_f32_e32 v48, v48, v49
	v_pk_fma_f32 v[50:51], v[50:51], v[50:51], v[52:53]
	v_mov_b32_e32 v52, v30
	v_mov_b32_e32 v53, v26
	v_pk_fma_f32 v[50:51], v[52:53], v[52:53], v[50:51]
	v_mov_b32_e32 v52, v31
	v_mov_b32_e32 v53, v27
	v_pk_fma_f32 v[50:51], v[52:53], v[52:53], v[50:51]
	v_ashrrev_i32_e32 v163, 31, v162
	v_add_f32_e32 v48, v48, v50
	v_add_f32_e32 v48, v48, v51
	v_mov_b32_e32 v49, v48
	v_lshlrev_b64 v[52:53], 11, v[162:163]
	v_lshl_add_u64 v[52:53], v[148:149], 0, v[52:53]
	s_nop 1
	v_permlane32_swap_b32_e32 v49, v48
	s_nop 1
	v_add_f32_e32 v48, v48, v49
	v_mov_b32_e32 v49, v48
	s_nop 1
	v_permlane16_swap_b32_e32 v49, v48
	s_nop 1
	v_add_f32_e32 v48, v48, v49
	s_nop 1
	v_add_f32_dpp v48, v48, v48 row_ror:8 row_mask:0xf bank_mask:0xf
	s_nop 1
	v_add_f32_dpp v48, v48, v48 row_ror:4 row_mask:0xf bank_mask:0xf
	s_nop 1
	v_add_f32_dpp v50, v48, v48 quad_perm:[2,3,0,1] row_mask:0xf bank_mask:0xf
	v_pk_add_f32 v[48:49], v[22:23], 1.0 op_sel_hi:[1,0]
	s_nop 1
	v_add_f32_dpp v50, v50, v50 quad_perm:[1,0,3,2] row_mask:0xf bank_mask:0xf
	v_fmamk_f32 v50, v50, 0x3a800000, v184
	v_rsq_f32_e32 v54, v50
	v_pk_add_f32 v[50:51], v[20:21], 1.0 op_sel_hi:[1,0]
	v_pk_mul_f32 v[38:39], v[38:39], v[54:55] op_sel_hi:[1,0]
	v_pk_mul_f32 v[36:37], v[36:37], v[54:55] op_sel_hi:[1,0]
	v_pk_mul_f32 v[38:39], v[2:3], v[38:39]
	v_pk_mul_f32 v[36:37], v[0:1], v[36:37]
	v_pk_fma_f32 v[38:39], v[48:49], v[38:39], v[18:19]
	v_pk_fma_f32 v[36:37], v[50:51], v[36:37], v[16:17]
	v_pk_mul_f32 v[34:35], v[34:35], v[54:55] op_sel_hi:[1,0]
	v_cvt_pk_bf16_f32 v36, v36, v37
	v_cvt_pk_bf16_f32 v37, v38, v39
	v_pk_mul_f32 v[32:33], v[32:33], v[54:55] op_sel_hi:[1,0]
	global_store_dwordx2 v[52:53], v[36:37], off
	v_pk_mul_f32 v[32:33], v[4:5], v[32:33]
	v_pk_mul_f32 v[34:35], v[6:7], v[34:35]
	v_pk_add_f32 v[36:37], v[46:47], 1.0 op_sel_hi:[1,0]
	v_pk_add_f32 v[38:39], v[44:45], 1.0 op_sel_hi:[1,0]
	v_pk_fma_f32 v[34:35], v[36:37], v[34:35], v[42:43]
	v_pk_fma_f32 v[32:33], v[38:39], v[32:33], v[40:41]
	v_pk_mul_f32 v[30:31], v[30:31], v[54:55] op_sel_hi:[1,0]
	v_cvt_pk_bf16_f32 v32, v32, v33
	v_cvt_pk_bf16_f32 v33, v34, v35
	v_pk_mul_f32 v[28:29], v[28:29], v[54:55] op_sel_hi:[1,0]
	global_store_dwordx2 v[52:53], v[32:33], off offset:512
	v_pk_mul_f32 v[28:29], v[8:9], v[28:29]
	v_pk_mul_f32 v[30:31], v[10:11], v[30:31]
	v_pk_add_f32 v[32:33], v[70:71], 1.0 op_sel_hi:[1,0]
	v_pk_add_f32 v[34:35], v[68:69], 1.0 op_sel_hi:[1,0]
	v_pk_fma_f32 v[30:31], v[32:33], v[30:31], v[66:67]
	v_pk_fma_f32 v[28:29], v[34:35], v[28:29], v[64:65]
	v_pk_mul_f32 v[26:27], v[26:27], v[54:55] op_sel_hi:[1,0]
	v_cvt_pk_bf16_f32 v28, v28, v29
	v_cvt_pk_bf16_f32 v29, v30, v31
	v_pk_mul_f32 v[24:25], v[24:25], v[54:55] op_sel_hi:[1,0]
	global_store_dwordx2 v[52:53], v[28:29], off offset:1024
	v_pk_mul_f32 v[24:25], v[12:13], v[24:25]
	v_pk_mul_f32 v[26:27], v[14:15], v[26:27]
	v_pk_add_f32 v[28:29], v[94:95], 1.0 op_sel_hi:[1,0]
	v_pk_add_f32 v[30:31], v[92:93], 1.0 op_sel_hi:[1,0]
	v_pk_fma_f32 v[26:27], v[28:29], v[26:27], v[90:91]
	v_pk_fma_f32 v[24:25], v[30:31], v[24:25], v[88:89]
	s_nop 0
	v_cvt_pk_bf16_f32 v24, v24, v25
	v_cvt_pk_bf16_f32 v25, v26, v27
	global_store_dwordx2 v[52:53], v[24:25], off offset:1536

.LBB0_111:
	s_or_b64 exec, exec, s[6:7]
	s_waitcnt vmcnt(23)
	v_mov_b32_e32 v174, v141
	s_waitcnt vmcnt(22)
	v_mov_b32_e32 v175, v137
	v_mov_b32_e32 v172, v140
	v_mov_b32_e32 v173, v136
	v_pk_mul_f32 v[174:175], v[174:175], v[174:175]
	s_waitcnt vmcnt(21)
	v_mov_b32_e32 v186, v133
	v_pk_fma_f32 v[172:173], v[172:173], v[172:173], v[174:175]
	v_mov_b32_e32 v174, v142
	v_mov_b32_e32 v175, v138
	v_pk_fma_f32 v[172:173], v[174:175], v[174:175], v[172:173]
	v_mov_b32_e32 v174, v143
	v_mov_b32_e32 v175, v139
	s_waitcnt vmcnt(20)
	v_mov_b32_e32 v187, v129
	v_pk_fma_f32 v[172:173], v[174:175], v[174:175], v[172:173]
	v_mov_b32_e32 v174, v132
	v_mov_b32_e32 v175, v128
	v_pk_mul_f32 v[186:187], v[186:187], v[186:187]
	v_add_f32_e32 v145, v172, v173
	v_pk_fma_f32 v[174:175], v[174:175], v[174:175], v[186:187]
	v_mov_b32_e32 v186, v134
	v_mov_b32_e32 v187, v130
	v_pk_fma_f32 v[174:175], v[186:187], v[186:187], v[174:175]
	v_mov_b32_e32 v186, v135
	v_mov_b32_e32 v187, v131
	v_pk_fma_f32 v[174:175], v[186:187], v[186:187], v[174:175]
	v_pk_add_f32 v[172:173], v[22:23], 1.0 op_sel_hi:[1,0]
	v_add_f32_e32 v145, v145, v174
	v_add_f32_e32 v145, v145, v175
	v_mov_b32_e32 v163, v145
	v_pk_add_f32 v[174:175], v[20:21], 1.0 op_sel_hi:[1,0]
	s_nop 1
	v_permlane32_swap_b32_e32 v163, v145
	s_nop 1
	v_add_f32_e32 v145, v145, v163
	v_mov_b32_e32 v163, v145
	s_nop 1
	v_permlane16_swap_b32_e32 v163, v145
	s_nop 1
	v_add_f32_e32 v145, v145, v163
	s_nop 1
	v_add_f32_dpp v145, v145, v145 row_ror:8 row_mask:0xf bank_mask:0xf
	s_nop 1
	v_add_f32_dpp v145, v145, v145 row_ror:4 row_mask:0xf bank_mask:0xf
	s_nop 1
	v_add_f32_dpp v163, v145, v145 quad_perm:[2,3,0,1] row_mask:0xf bank_mask:0xf
	v_ashrrev_i32_e32 v145, 31, v144
	v_lshlrev_b64 v[186:187], 11, v[144:145]
	v_lshl_add_u64 v[186:187], v[148:149], 0, v[186:187]
	s_nop 1
	v_add_f32_dpp v163, v163, v163 quad_perm:[1,0,3,2] row_mask:0xf bank_mask:0xf
	v_fmamk_f32 v163, v163, 0x3a800000, v184
	v_rsq_f32_e32 v163, v163
	s_nop 0
	v_mov_b32_e32 v188, v163
	v_pk_mul_f32 v[142:143], v[142:143], v[188:189] op_sel_hi:[1,0]
	v_pk_mul_f32 v[140:141], v[140:141], v[188:189] op_sel_hi:[1,0]
	v_pk_mul_f32 v[142:143], v[2:3], v[142:143]
	v_pk_mul_f32 v[140:141], v[0:1], v[140:141]
	v_pk_fma_f32 v[142:143], v[172:173], v[142:143], v[18:19]
	v_pk_fma_f32 v[140:141], v[174:175], v[140:141], v[16:17]
	v_pk_mul_f32 v[138:139], v[138:139], v[188:189] op_sel_hi:[1,0]
	v_cvt_pk_bf16_f32 v140, v140, v141
	v_cvt_pk_bf16_f32 v141, v142, v143
	v_pk_mul_f32 v[136:137], v[136:137], v[188:189] op_sel_hi:[1,0]
	global_store_dwordx2 v[186:187], v[140:141], off
	v_pk_mul_f32 v[140:141], v[4:5], v[136:137]
	v_pk_mul_f32 v[142:143], v[6:7], v[138:139]
	v_pk_add_f32 v[136:137], v[46:47], 1.0 op_sel_hi:[1,0]
	v_pk_add_f32 v[138:139], v[44:45], 1.0 op_sel_hi:[1,0]
	v_pk_fma_f32 v[142:143], v[136:137], v[142:143], v[42:43]
	v_pk_fma_f32 v[140:141], v[138:139], v[140:141], v[40:41]
	v_pk_mul_f32 v[134:135], v[134:135], v[188:189] op_sel_hi:[1,0]
	v_cvt_pk_bf16_f32 v140, v140, v141
	v_cvt_pk_bf16_f32 v141, v142, v143
	v_pk_mul_f32 v[132:133], v[132:133], v[188:189] op_sel_hi:[1,0]
	global_store_dwordx2 v[186:187], v[140:141], off offset:512
	v_pk_mul_f32 v[140:141], v[8:9], v[132:133]
	v_pk_mul_f32 v[142:143], v[10:11], v[134:135]
	v_pk_add_f32 v[132:133], v[70:71], 1.0 op_sel_hi:[1,0]
	v_pk_add_f32 v[134:135], v[68:69], 1.0 op_sel_hi:[1,0]
	v_pk_fma_f32 v[142:143], v[132:133], v[142:143], v[66:67]
	v_pk_fma_f32 v[140:141], v[134:135], v[140:141], v[64:65]
	v_pk_mul_f32 v[130:131], v[130:131], v[188:189] op_sel_hi:[1,0]
	v_cvt_pk_bf16_f32 v140, v140, v141
	v_cvt_pk_bf16_f32 v141, v142, v143
	v_pk_mul_f32 v[128:129], v[128:129], v[188:189] op_sel_hi:[1,0]
	global_store_dwordx2 v[186:187], v[140:141], off offset:1024
	v_pk_mul_f32 v[140:141], v[12:13], v[128:129]
	v_pk_mul_f32 v[142:143], v[14:15], v[130:131]
	v_pk_add_f32 v[128:129], v[94:95], 1.0 op_sel_hi:[1,0]
	v_pk_add_f32 v[130:131], v[92:93], 1.0 op_sel_hi:[1,0]
	v_pk_fma_f32 v[142:143], v[128:129], v[142:143], v[90:91]
	v_pk_fma_f32 v[140:141], v[130:131], v[140:141], v[88:89]
	v_cmp_lt_i32_e32 vcc, v170, v176
	v_cvt_pk_bf16_f32 v140, v140, v141
	v_cvt_pk_bf16_f32 v141, v142, v143
	global_store_dwordx2 v[186:187], v[140:141], off offset:1536
	s_and_saveexec_b64 s[6:7], vcc
	s_cbranch_execz .LBB0_136
	v_add_u32_e32 v140, 0xffffe001, v144
	v_ashrrev_i32_e32 v140, 10, v140
	v_add_u32_e32 v140, 1, v140
	v_cmp_lt_i32_e32 vcc, s15, v144
	s_nop 1
	v_cndmask_b32_e32 v140, 0, v140, vcc
	v_cmp_ne_u32_e32 vcc, v140, v185
	s_and_saveexec_b64 s[8:9], vcc
	s_cbranch_execz .LBB0_122
	global_load_dwordx4 v[16:19], v[150:151], off
	global_load_dwordx4 v[20:23], v[152:153], off
	v_mad_i64_i32 v[128:129], s[10:11], v140, s3, v[160:161]
	s_mov_b64 s[10:11], 0

.LBB0_122:
	s_or_b64 exec, exec, s[8:9]
	s_waitcnt vmcnt(23)
	v_mov_b32_e32 v142, v125
	s_waitcnt vmcnt(22)
	v_mov_b32_e32 v143, v121
	v_mov_b32_e32 v140, v124
	v_mov_b32_e32 v141, v120
	v_pk_mul_f32 v[142:143], v[142:143], v[142:143]
	s_waitcnt vmcnt(21)
	v_mov_b32_e32 v186, v117
	v_pk_fma_f32 v[140:141], v[140:141], v[140:141], v[142:143]
	v_mov_b32_e32 v142, v126
	v_mov_b32_e32 v143, v122
	v_pk_fma_f32 v[140:141], v[142:143], v[142:143], v[140:141]
	v_mov_b32_e32 v142, v127
	v_mov_b32_e32 v143, v123
	s_waitcnt vmcnt(20)
	v_mov_b32_e32 v187, v113
	v_pk_fma_f32 v[140:141], v[142:143], v[142:143], v[140:141]
	v_mov_b32_e32 v142, v116
	v_mov_b32_e32 v143, v112
	v_pk_mul_f32 v[186:187], v[186:187], v[186:187]
	v_add_f32_e32 v140, v140, v141
	v_pk_fma_f32 v[142:143], v[142:143], v[142:143], v[186:187]
	v_mov_b32_e32 v186, v118
	v_mov_b32_e32 v187, v114
	v_pk_fma_f32 v[142:143], v[186:187], v[186:187], v[142:143]
	v_mov_b32_e32 v186, v119
	v_mov_b32_e32 v187, v115
	v_pk_fma_f32 v[142:143], v[186:187], v[186:187], v[142:143]
	v_ashrrev_i32_e32 v171, 31, v170
	v_add_f32_e32 v140, v140, v142
	v_add_f32_e32 v140, v140, v143
	v_mov_b32_e32 v141, v140
	s_nop 1
	v_permlane32_swap_b32_e32 v141, v140
	s_nop 1
	v_add_f32_e32 v140, v140, v141
	v_mov_b32_e32 v141, v140
	s_nop 1
	v_permlane16_swap_b32_e32 v141, v140
	s_nop 1
	v_add_f32_e32 v140, v140, v141
	s_nop 1
	v_add_f32_dpp v140, v140, v140 row_ror:8 row_mask:0xf bank_mask:0xf
	s_nop 1
	v_add_f32_dpp v140, v140, v140 row_ror:4 row_mask:0xf bank_mask:0xf
	s_nop 1
	v_add_f32_dpp v140, v140, v140 quad_perm:[2,3,0,1] row_mask:0xf bank_mask:0xf
	s_nop 1
	v_add_f32_dpp v140, v140, v140 quad_perm:[1,0,3,2] row_mask:0xf bank_mask:0xf
	v_fmamk_f32 v140, v140, 0x3a800000, v184
	v_rsq_f32_e32 v142, v140
	v_lshlrev_b64 v[140:141], 11, v[170:171]
	v_lshl_add_u64 v[140:141], v[148:149], 0, v[140:141]
	v_pk_mul_f32 v[126:127], v[126:127], v[142:143] op_sel_hi:[1,0]
	v_pk_mul_f32 v[124:125], v[124:125], v[142:143] op_sel_hi:[1,0]
	v_pk_mul_f32 v[122:123], v[122:123], v[142:143] op_sel_hi:[1,0]
	v_pk_mul_f32 v[120:121], v[120:121], v[142:143] op_sel_hi:[1,0]
	v_pk_mul_f32 v[118:119], v[118:119], v[142:143] op_sel_hi:[1,0]
	v_pk_mul_f32 v[116:117], v[116:117], v[142:143] op_sel_hi:[1,0]
	v_pk_mul_f32 v[114:115], v[114:115], v[142:143] op_sel_hi:[1,0]
	v_pk_mul_f32 v[112:113], v[112:113], v[142:143] op_sel_hi:[1,0]
	v_pk_mul_f32 v[124:125], v[0:1], v[124:125]
	v_pk_mul_f32 v[126:127], v[2:3], v[126:127]
	v_pk_mul_f32 v[120:121], v[4:5], v[120:121]
	v_pk_mul_f32 v[122:123], v[6:7], v[122:123]
	v_pk_mul_f32 v[116:117], v[8:9], v[116:117]
	v_pk_mul_f32 v[118:119], v[10:11], v[118:119]
	v_pk_mul_f32 v[112:113], v[12:13], v[112:113]
	v_pk_mul_f32 v[114:115], v[14:15], v[114:115]
	v_pk_fma_f32 v[126:127], v[172:173], v[126:127], v[18:19]
	v_pk_fma_f32 v[124:125], v[174:175], v[124:125], v[16:17]
	v_pk_fma_f32 v[122:123], v[136:137], v[122:123], v[42:43]
	v_pk_fma_f32 v[120:121], v[138:139], v[120:121], v[40:41]
	v_pk_fma_f32 v[118:119], v[132:133], v[118:119], v[66:67]
	v_pk_fma_f32 v[116:117], v[134:135], v[116:117], v[64:65]
	v_pk_fma_f32 v[114:115], v[128:129], v[114:115], v[90:91]
	v_pk_fma_f32 v[112:113], v[130:131], v[112:113], v[88:89]
	v_cvt_pk_bf16_f32 v124, v124, v125
	v_cvt_pk_bf16_f32 v125, v126, v127
	v_cvt_pk_bf16_f32 v120, v120, v121
	v_cvt_pk_bf16_f32 v121, v122, v123
	v_cvt_pk_bf16_f32 v116, v116, v117
	v_cvt_pk_bf16_f32 v117, v118, v119
	v_cvt_pk_bf16_f32 v112, v112, v113
	v_cvt_pk_bf16_f32 v113, v114, v115
	global_store_dwordx2 v[140:141], v[124:125], off
	global_store_dwordx2 v[140:141], v[120:121], off offset:512
	global_store_dwordx2 v[140:141], v[116:117], off offset:1024
	global_store_dwordx2 v[140:141], v[112:113], off offset:1536
	s_or_b64 exec, exec, s[6:7]
	v_cmp_lt_i32_e32 vcc, v168, v176
	s_and_saveexec_b64 s[6:7], vcc
	s_cbranch_execnz .LBB0_137

.LBB0_134:
	s_or_b64 exec, exec, s[8:9]
	s_waitcnt vmcnt(15)
	v_mov_b32_e32 v98, v85
	s_waitcnt vmcnt(14)
	v_mov_b32_e32 v99, v81
	v_mov_b32_e32 v96, v84
	v_mov_b32_e32 v97, v80
	v_pk_mul_f32 v[98:99], v[98:99], v[98:99]
	s_waitcnt vmcnt(13)
	v_mov_b32_e32 v100, v77
	v_pk_fma_f32 v[96:97], v[96:97], v[96:97], v[98:99]
	v_mov_b32_e32 v98, v86
	v_mov_b32_e32 v99, v82
	v_pk_fma_f32 v[96:97], v[98:99], v[98:99], v[96:97]
	v_mov_b32_e32 v98, v87
	v_mov_b32_e32 v99, v83
	s_waitcnt vmcnt(12)
	v_mov_b32_e32 v101, v73
	v_pk_fma_f32 v[96:97], v[98:99], v[98:99], v[96:97]
	v_mov_b32_e32 v98, v76
	v_mov_b32_e32 v99, v72
	v_pk_mul_f32 v[100:101], v[100:101], v[100:101]
	v_add_f32_e32 v96, v96, v97
	v_pk_fma_f32 v[98:99], v[98:99], v[98:99], v[100:101]
	v_mov_b32_e32 v100, v78
	v_mov_b32_e32 v101, v74
	v_pk_fma_f32 v[98:99], v[100:101], v[100:101], v[98:99]
	v_mov_b32_e32 v100, v79
	v_mov_b32_e32 v101, v75
	v_pk_fma_f32 v[98:99], v[100:101], v[100:101], v[98:99]
	v_ashrrev_i32_e32 v167, 31, v166
	v_add_f32_e32 v96, v96, v98
	v_add_f32_e32 v96, v96, v99
	v_mov_b32_e32 v97, v96
	v_lshlrev_b64 v[100:101], 11, v[166:167]
	v_lshl_add_u64 v[100:101], v[148:149], 0, v[100:101]
	s_nop 1
	v_permlane32_swap_b32_e32 v97, v96
	s_nop 1
	v_add_f32_e32 v96, v96, v97
	v_mov_b32_e32 v97, v96
	s_nop 1
	v_permlane16_swap_b32_e32 v97, v96
	s_nop 1
	v_add_f32_e32 v96, v96, v97
	s_nop 1
	v_add_f32_dpp v96, v96, v96 row_ror:8 row_mask:0xf bank_mask:0xf
	s_nop 1
	v_add_f32_dpp v96, v96, v96 row_ror:4 row_mask:0xf bank_mask:0xf
	s_nop 1
	v_add_f32_dpp v98, v96, v96 quad_perm:[2,3,0,1] row_mask:0xf bank_mask:0xf
	v_pk_add_f32 v[96:97], v[22:23], 1.0 op_sel_hi:[1,0]
	s_nop 1
	v_add_f32_dpp v98, v98, v98 quad_perm:[1,0,3,2] row_mask:0xf bank_mask:0xf
	v_fmamk_f32 v98, v98, 0x3a800000, v184
	v_rsq_f32_e32 v102, v98
	v_pk_add_f32 v[98:99], v[20:21], 1.0 op_sel_hi:[1,0]
	v_pk_mul_f32 v[86:87], v[86:87], v[102:103] op_sel_hi:[1,0]
	v_pk_mul_f32 v[84:85], v[84:85], v[102:103] op_sel_hi:[1,0]
	v_pk_mul_f32 v[86:87], v[2:3], v[86:87]
	v_pk_mul_f32 v[84:85], v[0:1], v[84:85]
	v_pk_fma_f32 v[86:87], v[96:97], v[86:87], v[18:19]
	v_pk_fma_f32 v[84:85], v[98:99], v[84:85], v[16:17]
	v_pk_mul_f32 v[82:83], v[82:83], v[102:103] op_sel_hi:[1,0]
	v_cvt_pk_bf16_f32 v84, v84, v85
	v_cvt_pk_bf16_f32 v85, v86, v87
	v_pk_mul_f32 v[80:81], v[80:81], v[102:103] op_sel_hi:[1,0]
	global_store_dwordx2 v[100:101], v[84:85], off
	v_pk_mul_f32 v[80:81], v[4:5], v[80:81]
	v_pk_mul_f32 v[82:83], v[6:7], v[82:83]
	v_pk_add_f32 v[84:85], v[46:47], 1.0 op_sel_hi:[1,0]
	v_pk_add_f32 v[86:87], v[44:45], 1.0 op_sel_hi:[1,0]
	v_pk_fma_f32 v[82:83], v[84:85], v[82:83], v[42:43]
	v_pk_fma_f32 v[80:81], v[86:87], v[80:81], v[40:41]
	v_pk_mul_f32 v[78:79], v[78:79], v[102:103] op_sel_hi:[1,0]
	v_cvt_pk_bf16_f32 v80, v80, v81
	v_cvt_pk_bf16_f32 v81, v82, v83
	v_pk_mul_f32 v[76:77], v[76:77], v[102:103] op_sel_hi:[1,0]
	global_store_dwordx2 v[100:101], v[80:81], off offset:512
	v_pk_mul_f32 v[76:77], v[8:9], v[76:77]
	v_pk_mul_f32 v[78:79], v[10:11], v[78:79]
	v_pk_add_f32 v[80:81], v[70:71], 1.0 op_sel_hi:[1,0]
	v_pk_add_f32 v[82:83], v[68:69], 1.0 op_sel_hi:[1,0]
	v_pk_fma_f32 v[78:79], v[80:81], v[78:79], v[66:67]
	v_pk_fma_f32 v[76:77], v[82:83], v[76:77], v[64:65]
	v_pk_mul_f32 v[74:75], v[74:75], v[102:103] op_sel_hi:[1,0]
	v_cvt_pk_bf16_f32 v76, v76, v77
	v_cvt_pk_bf16_f32 v77, v78, v79
	v_pk_mul_f32 v[72:73], v[72:73], v[102:103] op_sel_hi:[1,0]
	global_store_dwordx2 v[100:101], v[76:77], off offset:1024
	v_pk_mul_f32 v[72:73], v[12:13], v[72:73]
	v_pk_mul_f32 v[74:75], v[14:15], v[74:75]
	v_pk_add_f32 v[76:77], v[94:95], 1.0 op_sel_hi:[1,0]
	v_pk_add_f32 v[78:79], v[92:93], 1.0 op_sel_hi:[1,0]
	v_pk_fma_f32 v[74:75], v[76:77], v[74:75], v[90:91]
	v_pk_fma_f32 v[72:73], v[78:79], v[72:73], v[88:89]
	s_nop 0
	v_cvt_pk_bf16_f32 v72, v72, v73
	v_cvt_pk_bf16_f32 v73, v74, v75
	global_store_dwordx2 v[100:101], v[72:73], off offset:1536
	s_or_b64 exec, exec, s[6:7]
	v_cmp_lt_i32_e32 vcc, v164, v176
	s_and_saveexec_b64 s[6:7], vcc
	s_cbranch_execnz .LBB0_149

.LBB0_147:
	s_or_b64 exec, exec, s[8:9]
	s_waitcnt vmcnt(19)
	v_mov_b32_e32 v114, v109
	s_waitcnt vmcnt(18)
	v_mov_b32_e32 v115, v105
	v_mov_b32_e32 v112, v108
	v_mov_b32_e32 v113, v104
	v_pk_mul_f32 v[114:115], v[114:115], v[114:115]
	s_waitcnt vmcnt(17)
	v_mov_b32_e32 v116, v101
	v_pk_fma_f32 v[112:113], v[112:113], v[112:113], v[114:115]
	v_mov_b32_e32 v114, v110
	v_mov_b32_e32 v115, v106
	v_pk_fma_f32 v[112:113], v[114:115], v[114:115], v[112:113]
	v_mov_b32_e32 v114, v111
	v_mov_b32_e32 v115, v107
	s_waitcnt vmcnt(16)
	v_mov_b32_e32 v117, v97
	v_pk_fma_f32 v[112:113], v[114:115], v[114:115], v[112:113]
	v_mov_b32_e32 v114, v100
	v_mov_b32_e32 v115, v96
	v_pk_mul_f32 v[116:117], v[116:117], v[116:117]
	v_add_f32_e32 v112, v112, v113
	v_pk_fma_f32 v[114:115], v[114:115], v[114:115], v[116:117]
	v_mov_b32_e32 v116, v102
	v_mov_b32_e32 v117, v98
	v_pk_fma_f32 v[114:115], v[116:117], v[116:117], v[114:115]
	v_mov_b32_e32 v116, v103
	v_mov_b32_e32 v117, v99
	v_pk_fma_f32 v[114:115], v[116:117], v[116:117], v[114:115]
	v_ashrrev_i32_e32 v169, 31, v168
	v_add_f32_e32 v112, v112, v114
	v_add_f32_e32 v112, v112, v115
	v_mov_b32_e32 v113, v112
	v_lshlrev_b64 v[116:117], 11, v[168:169]
	v_lshl_add_u64 v[116:117], v[148:149], 0, v[116:117]
	s_nop 1
	v_permlane32_swap_b32_e32 v113, v112
	s_nop 1
	v_add_f32_e32 v112, v112, v113
	v_mov_b32_e32 v113, v112
	s_nop 1
	v_permlane16_swap_b32_e32 v113, v112
	s_nop 1
	v_add_f32_e32 v112, v112, v113
	s_nop 1
	v_add_f32_dpp v112, v112, v112 row_ror:8 row_mask:0xf bank_mask:0xf
	s_nop 1
	v_add_f32_dpp v112, v112, v112 row_ror:4 row_mask:0xf bank_mask:0xf
	s_nop 1
	v_add_f32_dpp v114, v112, v112 quad_perm:[2,3,0,1] row_mask:0xf bank_mask:0xf
	v_pk_add_f32 v[112:113], v[22:23], 1.0 op_sel_hi:[1,0]
	s_nop 1
	v_add_f32_dpp v114, v114, v114 quad_perm:[1,0,3,2] row_mask:0xf bank_mask:0xf
	v_fmamk_f32 v114, v114, 0x3a800000, v184
	v_rsq_f32_e32 v118, v114
	v_pk_add_f32 v[114:115], v[20:21], 1.0 op_sel_hi:[1,0]
	v_pk_mul_f32 v[110:111], v[110:111], v[118:119] op_sel_hi:[1,0]
	v_pk_mul_f32 v[108:109], v[108:109], v[118:119] op_sel_hi:[1,0]
	v_pk_mul_f32 v[110:111], v[2:3], v[110:111]
	v_pk_mul_f32 v[108:109], v[0:1], v[108:109]
	v_pk_fma_f32 v[110:111], v[112:113], v[110:111], v[18:19]
	v_pk_fma_f32 v[108:109], v[114:115], v[108:109], v[16:17]
	v_pk_mul_f32 v[106:107], v[106:107], v[118:119] op_sel_hi:[1,0]
	v_cvt_pk_bf16_f32 v108, v108, v109
	v_cvt_pk_bf16_f32 v109, v110, v111
	v_pk_mul_f32 v[104:105], v[104:105], v[118:119] op_sel_hi:[1,0]
	global_store_dwordx2 v[116:117], v[108:109], off
	v_pk_mul_f32 v[104:105], v[4:5], v[104:105]
	v_pk_mul_f32 v[106:107], v[6:7], v[106:107]
	v_pk_add_f32 v[108:109], v[46:47], 1.0 op_sel_hi:[1,0]
	v_pk_add_f32 v[110:111], v[44:45], 1.0 op_sel_hi:[1,0]
	v_pk_fma_f32 v[106:107], v[108:109], v[106:107], v[42:43]
	v_pk_fma_f32 v[104:105], v[110:111], v[104:105], v[40:41]
	v_pk_mul_f32 v[102:103], v[102:103], v[118:119] op_sel_hi:[1,0]
	v_cvt_pk_bf16_f32 v104, v104, v105
	v_cvt_pk_bf16_f32 v105, v106, v107
	v_pk_mul_f32 v[100:101], v[100:101], v[118:119] op_sel_hi:[1,0]
	global_store_dwordx2 v[116:117], v[104:105], off offset:512
	v_pk_mul_f32 v[100:101], v[8:9], v[100:101]
	v_pk_mul_f32 v[102:103], v[10:11], v[102:103]
	v_pk_add_f32 v[104:105], v[70:71], 1.0 op_sel_hi:[1,0]
	v_pk_add_f32 v[106:107], v[68:69], 1.0 op_sel_hi:[1,0]
	v_pk_fma_f32 v[102:103], v[104:105], v[102:103], v[66:67]
	v_pk_fma_f32 v[100:101], v[106:107], v[100:101], v[64:65]
	v_pk_mul_f32 v[98:99], v[98:99], v[118:119] op_sel_hi:[1,0]
	v_cvt_pk_bf16_f32 v100, v100, v101
	v_cvt_pk_bf16_f32 v101, v102, v103
	v_pk_mul_f32 v[96:97], v[96:97], v[118:119] op_sel_hi:[1,0]
	global_store_dwordx2 v[116:117], v[100:101], off offset:1024
	v_pk_mul_f32 v[96:97], v[12:13], v[96:97]
	v_pk_mul_f32 v[98:99], v[14:15], v[98:99]
	v_pk_add_f32 v[100:101], v[94:95], 1.0 op_sel_hi:[1,0]
	v_pk_add_f32 v[102:103], v[92:93], 1.0 op_sel_hi:[1,0]
	v_pk_fma_f32 v[98:99], v[100:101], v[98:99], v[90:91]
	v_pk_fma_f32 v[96:97], v[102:103], v[96:97], v[88:89]
	s_nop 0
	v_cvt_pk_bf16_f32 v96, v96, v97
	v_cvt_pk_bf16_f32 v97, v98, v99
	global_store_dwordx2 v[116:117], v[96:97], off offset:1536
	s_or_b64 exec, exec, s[6:7]
	v_cmp_lt_i32_e32 vcc, v166, v176
	s_and_saveexec_b64 s[6:7], vcc
	s_cbranch_execnz .LBB0_124

.LBB0_159:
	s_or_b64 exec, exec, s[8:9]
	s_waitcnt vmcnt(11)
	v_mov_b32_e32 v74, v61
	s_waitcnt vmcnt(10)
	v_mov_b32_e32 v75, v57
	v_mov_b32_e32 v72, v60
	v_mov_b32_e32 v73, v56
	v_pk_mul_f32 v[74:75], v[74:75], v[74:75]
	s_waitcnt vmcnt(9)
	v_mov_b32_e32 v76, v53
	v_pk_fma_f32 v[72:73], v[72:73], v[72:73], v[74:75]
	v_mov_b32_e32 v74, v62
	v_mov_b32_e32 v75, v58
	v_pk_fma_f32 v[72:73], v[74:75], v[74:75], v[72:73]
	v_mov_b32_e32 v74, v63
	v_mov_b32_e32 v75, v59
	s_waitcnt vmcnt(8)
	v_mov_b32_e32 v77, v49
	v_pk_fma_f32 v[72:73], v[74:75], v[74:75], v[72:73]
	v_mov_b32_e32 v74, v52
	v_mov_b32_e32 v75, v48
	v_pk_mul_f32 v[76:77], v[76:77], v[76:77]
	v_add_f32_e32 v72, v72, v73
	v_pk_fma_f32 v[74:75], v[74:75], v[74:75], v[76:77]
	v_mov_b32_e32 v76, v54
	v_mov_b32_e32 v77, v50
	v_pk_fma_f32 v[74:75], v[76:77], v[76:77], v[74:75]
	v_mov_b32_e32 v76, v55
	v_mov_b32_e32 v77, v51
	v_pk_fma_f32 v[74:75], v[76:77], v[76:77], v[74:75]
	v_ashrrev_i32_e32 v165, 31, v164
	v_add_f32_e32 v72, v72, v74
	v_add_f32_e32 v72, v72, v75
	v_mov_b32_e32 v73, v72
	v_lshlrev_b64 v[76:77], 11, v[164:165]
	v_lshl_add_u64 v[76:77], v[148:149], 0, v[76:77]
	s_nop 1
	v_permlane32_swap_b32_e32 v73, v72
	s_nop 1
	v_add_f32_e32 v72, v72, v73
	v_mov_b32_e32 v73, v72
	s_nop 1
	v_permlane16_swap_b32_e32 v73, v72
	s_nop 1
	v_add_f32_e32 v72, v72, v73
	s_nop 1
	v_add_f32_dpp v72, v72, v72 row_ror:8 row_mask:0xf bank_mask:0xf
	s_nop 1
	v_add_f32_dpp v72, v72, v72 row_ror:4 row_mask:0xf bank_mask:0xf
	s_nop 1
	v_add_f32_dpp v74, v72, v72 quad_perm:[2,3,0,1] row_mask:0xf bank_mask:0xf
	v_pk_add_f32 v[72:73], v[22:23], 1.0 op_sel_hi:[1,0]
	s_nop 1
	v_add_f32_dpp v74, v74, v74 quad_perm:[1,0,3,2] row_mask:0xf bank_mask:0xf
	v_fmamk_f32 v74, v74, 0x3a800000, v184
	v_rsq_f32_e32 v78, v74
	v_pk_add_f32 v[74:75], v[20:21], 1.0 op_sel_hi:[1,0]
	v_pk_mul_f32 v[62:63], v[62:63], v[78:79] op_sel_hi:[1,0]
	v_pk_mul_f32 v[60:61], v[60:61], v[78:79] op_sel_hi:[1,0]
	v_pk_mul_f32 v[62:63], v[2:3], v[62:63]
	v_pk_mul_f32 v[60:61], v[0:1], v[60:61]
	v_pk_fma_f32 v[62:63], v[72:73], v[62:63], v[18:19]
	v_pk_fma_f32 v[60:61], v[74:75], v[60:61], v[16:17]
	v_pk_mul_f32 v[58:59], v[58:59], v[78:79] op_sel_hi:[1,0]
	v_cvt_pk_bf16_f32 v60, v60, v61
	v_cvt_pk_bf16_f32 v61, v62, v63
	v_pk_mul_f32 v[56:57], v[56:57], v[78:79] op_sel_hi:[1,0]
	global_store_dwordx2 v[76:77], v[60:61], off
	v_pk_mul_f32 v[56:57], v[4:5], v[56:57]
	v_pk_mul_f32 v[58:59], v[6:7], v[58:59]
	v_pk_add_f32 v[60:61], v[46:47], 1.0 op_sel_hi:[1,0]
	v_pk_add_f32 v[62:63], v[44:45], 1.0 op_sel_hi:[1,0]
	v_pk_fma_f32 v[58:59], v[60:61], v[58:59], v[42:43]
	v_pk_fma_f32 v[56:57], v[62:63], v[56:57], v[40:41]
	v_pk_mul_f32 v[54:55], v[54:55], v[78:79] op_sel_hi:[1,0]
	v_cvt_pk_bf16_f32 v56, v56, v57
	v_cvt_pk_bf16_f32 v57, v58, v59
	v_pk_mul_f32 v[52:53], v[52:53], v[78:79] op_sel_hi:[1,0]
	global_store_dwordx2 v[76:77], v[56:57], off offset:512
	v_pk_mul_f32 v[52:53], v[8:9], v[52:53]
	v_pk_mul_f32 v[54:55], v[10:11], v[54:55]
	v_pk_add_f32 v[56:57], v[70:71], 1.0 op_sel_hi:[1,0]
	v_pk_add_f32 v[58:59], v[68:69], 1.0 op_sel_hi:[1,0]
	v_pk_fma_f32 v[54:55], v[56:57], v[54:55], v[66:67]
	v_pk_fma_f32 v[52:53], v[58:59], v[52:53], v[64:65]
	v_pk_mul_f32 v[50:51], v[50:51], v[78:79] op_sel_hi:[1,0]
	v_cvt_pk_bf16_f32 v52, v52, v53
	v_cvt_pk_bf16_f32 v53, v54, v55
	v_pk_mul_f32 v[48:49], v[48:49], v[78:79] op_sel_hi:[1,0]
	global_store_dwordx2 v[76:77], v[52:53], off offset:1024
	v_pk_mul_f32 v[48:49], v[12:13], v[48:49]
	v_pk_mul_f32 v[50:51], v[14:15], v[50:51]
	v_pk_add_f32 v[52:53], v[94:95], 1.0 op_sel_hi:[1,0]
	v_pk_add_f32 v[54:55], v[92:93], 1.0 op_sel_hi:[1,0]
	v_pk_fma_f32 v[50:51], v[52:53], v[50:51], v[90:91]
	v_pk_fma_f32 v[48:49], v[54:55], v[48:49], v[88:89]
	s_nop 0
	v_cvt_pk_bf16_f32 v48, v48, v49
	v_cvt_pk_bf16_f32 v49, v50, v51
	global_store_dwordx2 v[76:77], v[48:49], off offset:1536
	s_or_b64 exec, exec, s[6:7]
	v_cmp_lt_i32_e32 vcc, v162, v176
	s_and_saveexec_b64 s[6:7], vcc
	s_cbranch_execz .LBB0_100

.LBB0_1130:
	s_or_b64 exec, exec, s[40:41]
	v_mov_b32_e32 v60, v45
	v_mov_b32_e32 v61, v41
	v_mov_b32_e32 v58, v44
	v_mov_b32_e32 v59, v40
	v_pk_mul_f32 v[60:61], v[60:61], v[60:61]
	v_mov_b32_e32 v62, v37
	v_pk_fma_f32 v[58:59], v[58:59], v[58:59], v[60:61]
	v_mov_b32_e32 v60, v46
	v_mov_b32_e32 v61, v42
	v_pk_fma_f32 v[58:59], v[60:61], v[60:61], v[58:59]
	v_mov_b32_e32 v60, v47
	v_mov_b32_e32 v61, v43
	v_mov_b32_e32 v63, v33
	v_pk_fma_f32 v[58:59], v[60:61], v[60:61], v[58:59]
	v_mov_b32_e32 v60, v36
	v_mov_b32_e32 v61, v32
	v_pk_mul_f32 v[62:63], v[62:63], v[62:63]
	v_add_f32_e32 v58, v58, v59
	v_pk_fma_f32 v[60:61], v[60:61], v[60:61], v[62:63]
	v_mov_b32_e32 v62, v38
	v_mov_b32_e32 v63, v34
	v_pk_fma_f32 v[60:61], v[62:63], v[62:63], v[60:61]
	v_mov_b32_e32 v62, v39
	v_mov_b32_e32 v63, v35
	v_pk_fma_f32 v[60:61], v[62:63], v[62:63], v[60:61]
	v_lshl_add_u64 v[56:57], v[132:133], 0, v[56:57]
	v_add_f32_e32 v58, v58, v60
	v_add_f32_e32 v58, v58, v61
	v_mov_b32_e32 v59, v58
	v_pk_add_f32 v[60:61], v[20:21], 1.0 op_sel_hi:[1,0]
	s_nop 1
	v_permlane32_swap_b32_e32 v59, v58
	s_nop 1
	v_add_f32_e32 v58, v58, v59
	v_mov_b32_e32 v59, v58
	s_nop 1
	v_permlane16_swap_b32_e32 v59, v58
	s_nop 1
	v_add_f32_e32 v58, v58, v59
	s_nop 1
	v_add_f32_dpp v58, v58, v58 row_ror:8 row_mask:0xf bank_mask:0xf
	s_nop 1
	v_add_f32_dpp v58, v58, v58 row_ror:4 row_mask:0xf bank_mask:0xf
	s_nop 1
	v_add_f32_dpp v58, v58, v58 quad_perm:[2,3,0,1] row_mask:0xf bank_mask:0xf
	s_nop 1
	v_add_f32_dpp v58, v58, v58 quad_perm:[1,0,3,2] row_mask:0xf bank_mask:0xf
	v_fmamk_f32 v58, v58, 0x3a800000, v234
	v_rsq_f32_e32 v62, v58
	v_pk_add_f32 v[58:59], v[22:23], 1.0 op_sel_hi:[1,0]
	v_pk_mul_f32 v[46:47], v[46:47], v[62:63] op_sel_hi:[1,0]
	v_pk_mul_f32 v[44:45], v[44:45], v[62:63] op_sel_hi:[1,0]
	v_pk_mul_f32 v[46:47], v[10:11], v[46:47]
	v_pk_mul_f32 v[44:45], v[8:9], v[44:45]
	v_pk_fma_f32 v[46:47], v[58:59], v[46:47], v[18:19]
	v_pk_fma_f32 v[44:45], v[60:61], v[44:45], v[16:17]
	v_pk_mul_f32 v[42:43], v[42:43], v[62:63] op_sel_hi:[1,0]
	v_cvt_pk_bf16_f32 v44, v44, v45
	v_cvt_pk_bf16_f32 v45, v46, v47
	v_pk_mul_f32 v[40:41], v[40:41], v[62:63] op_sel_hi:[1,0]
	global_store_dwordx2 v[56:57], v[44:45], off
	v_pk_mul_f32 v[40:41], v[0:1], v[40:41]
	v_pk_mul_f32 v[42:43], v[2:3], v[42:43]
	v_pk_add_f32 v[44:45], v[30:31], 1.0 op_sel_hi:[1,0]
	v_pk_add_f32 v[46:47], v[28:29], 1.0 op_sel_hi:[1,0]
	v_pk_fma_f32 v[42:43], v[44:45], v[42:43], v[26:27]
	v_pk_fma_f32 v[40:41], v[46:47], v[40:41], v[24:25]
	v_pk_mul_f32 v[38:39], v[38:39], v[62:63] op_sel_hi:[1,0]
	v_cvt_pk_bf16_f32 v40, v40, v41
	v_cvt_pk_bf16_f32 v41, v42, v43
	v_pk_mul_f32 v[36:37], v[36:37], v[62:63] op_sel_hi:[1,0]
	global_store_dwordx2 v[56:57], v[40:41], off offset:512
	v_pk_mul_f32 v[36:37], v[4:5], v[36:37]
	v_pk_mul_f32 v[38:39], v[6:7], v[38:39]
	v_pk_add_f32 v[40:41], v[54:55], 1.0 op_sel_hi:[1,0]
	v_pk_add_f32 v[42:43], v[52:53], 1.0 op_sel_hi:[1,0]
	v_pk_fma_f32 v[38:39], v[40:41], v[38:39], v[50:51]
	v_pk_fma_f32 v[36:37], v[42:43], v[36:37], v[48:49]
	v_pk_mul_f32 v[34:35], v[34:35], v[62:63] op_sel_hi:[1,0]
	v_cvt_pk_bf16_f32 v36, v36, v37
	v_cvt_pk_bf16_f32 v37, v38, v39
	v_pk_mul_f32 v[32:33], v[32:33], v[62:63] op_sel_hi:[1,0]
	global_store_dwordx2 v[56:57], v[36:37], off offset:1024
	v_pk_mul_f32 v[32:33], v[12:13], v[32:33]
	v_pk_mul_f32 v[34:35], v[14:15], v[34:35]
	v_pk_add_f32 v[36:37], v[78:79], 1.0 op_sel_hi:[1,0]
	v_pk_add_f32 v[38:39], v[76:77], 1.0 op_sel_hi:[1,0]
	v_pk_fma_f32 v[34:35], v[36:37], v[34:35], v[74:75]
	v_pk_fma_f32 v[32:33], v[38:39], v[32:33], v[72:73]
	s_nop 0
	v_cvt_pk_bf16_f32 v32, v32, v33
	v_cvt_pk_bf16_f32 v33, v34, v35
	global_store_dwordx2 v[56:57], v[32:33], off offset:1536

.LBB0_1142:
	s_or_b64 exec, exec, s[6:7]
	v_mov_b32_e32 v236, v217
	v_mov_b32_e32 v237, v213
	v_mov_b32_e32 v222, v216
	v_mov_b32_e32 v223, v212
	v_pk_mul_f32 v[236:237], v[236:237], v[236:237]
	v_mov_b32_e32 v238, v209
	v_pk_fma_f32 v[222:223], v[222:223], v[222:223], v[236:237]
	v_mov_b32_e32 v236, v218
	v_mov_b32_e32 v237, v214
	v_pk_fma_f32 v[222:223], v[236:237], v[236:237], v[222:223]
	v_mov_b32_e32 v236, v219
	v_mov_b32_e32 v237, v215
	v_mov_b32_e32 v239, v205
	v_pk_fma_f32 v[222:223], v[236:237], v[236:237], v[222:223]
	v_mov_b32_e32 v236, v208
	v_mov_b32_e32 v237, v204
	v_pk_mul_f32 v[238:239], v[238:239], v[238:239]
	v_add_f32_e32 v129, v222, v223
	v_pk_fma_f32 v[236:237], v[236:237], v[236:237], v[238:239]
	v_mov_b32_e32 v238, v210
	v_mov_b32_e32 v239, v206
	v_pk_fma_f32 v[236:237], v[238:239], v[238:239], v[236:237]
	v_mov_b32_e32 v238, v211
	v_mov_b32_e32 v239, v207
	v_pk_fma_f32 v[236:237], v[238:239], v[238:239], v[236:237]
	v_pk_add_f32 v[222:223], v[20:21], 1.0 op_sel_hi:[1,0]
	v_add_f32_e32 v129, v129, v236
	v_add_f32_e32 v129, v129, v237
	v_mov_b32_e32 v155, v129
	v_lshl_add_u64 v[236:237], v[132:133], 0, v[220:221]
	v_pk_add_f32 v[220:221], v[22:23], 1.0 op_sel_hi:[1,0]
	s_nop 1
	v_permlane32_swap_b32_e32 v155, v129
	s_nop 1
	v_add_f32_e32 v129, v129, v155
	v_mov_b32_e32 v155, v129
	s_nop 1
	v_permlane16_swap_b32_e32 v155, v129
	s_nop 1
	v_add_f32_e32 v129, v129, v155
	s_nop 1
	v_add_f32_dpp v129, v129, v129 row_ror:8 row_mask:0xf bank_mask:0xf
	s_nop 1
	v_add_f32_dpp v129, v129, v129 row_ror:4 row_mask:0xf bank_mask:0xf
	s_nop 1
	v_add_f32_dpp v129, v129, v129 quad_perm:[2,3,0,1] row_mask:0xf bank_mask:0xf
	s_nop 1
	v_add_f32_dpp v129, v129, v129 quad_perm:[1,0,3,2] row_mask:0xf bank_mask:0xf
	v_fmamk_f32 v129, v129, 0x3a800000, v234
	v_rsq_f32_e32 v129, v129
	s_nop 0
	v_mov_b32_e32 v238, v129
	v_pk_mul_f32 v[218:219], v[218:219], v[238:239] op_sel_hi:[1,0]
	v_pk_mul_f32 v[216:217], v[216:217], v[238:239] op_sel_hi:[1,0]
	v_pk_mul_f32 v[218:219], v[10:11], v[218:219]
	v_pk_mul_f32 v[216:217], v[8:9], v[216:217]
	v_pk_fma_f32 v[218:219], v[220:221], v[218:219], v[18:19]
	v_pk_fma_f32 v[216:217], v[222:223], v[216:217], v[16:17]
	v_pk_mul_f32 v[214:215], v[214:215], v[238:239] op_sel_hi:[1,0]
	v_cvt_pk_bf16_f32 v216, v216, v217
	v_cvt_pk_bf16_f32 v217, v218, v219
	v_pk_mul_f32 v[212:213], v[212:213], v[238:239] op_sel_hi:[1,0]
	global_store_dwordx2 v[236:237], v[216:217], off
	v_pk_mul_f32 v[216:217], v[0:1], v[212:213]
	v_pk_mul_f32 v[218:219], v[2:3], v[214:215]
	v_pk_add_f32 v[212:213], v[30:31], 1.0 op_sel_hi:[1,0]
	v_pk_add_f32 v[214:215], v[28:29], 1.0 op_sel_hi:[1,0]
	v_pk_fma_f32 v[218:219], v[212:213], v[218:219], v[26:27]
	v_pk_fma_f32 v[216:217], v[214:215], v[216:217], v[24:25]
	v_pk_mul_f32 v[210:211], v[210:211], v[238:239] op_sel_hi:[1,0]
	v_cvt_pk_bf16_f32 v216, v216, v217
	v_cvt_pk_bf16_f32 v217, v218, v219
	v_pk_mul_f32 v[208:209], v[208:209], v[238:239] op_sel_hi:[1,0]
	global_store_dwordx2 v[236:237], v[216:217], off offset:512
	v_pk_mul_f32 v[216:217], v[4:5], v[208:209]
	v_pk_mul_f32 v[218:219], v[6:7], v[210:211]
	v_pk_add_f32 v[208:209], v[54:55], 1.0 op_sel_hi:[1,0]
	v_pk_add_f32 v[210:211], v[52:53], 1.0 op_sel_hi:[1,0]
	v_pk_fma_f32 v[218:219], v[208:209], v[218:219], v[50:51]
	v_pk_fma_f32 v[216:217], v[210:211], v[216:217], v[48:49]
	v_pk_mul_f32 v[206:207], v[206:207], v[238:239] op_sel_hi:[1,0]
	v_cvt_pk_bf16_f32 v216, v216, v217
	v_cvt_pk_bf16_f32 v217, v218, v219
	v_pk_mul_f32 v[204:205], v[204:205], v[238:239] op_sel_hi:[1,0]
	global_store_dwordx2 v[236:237], v[216:217], off offset:1024
	v_pk_mul_f32 v[216:217], v[12:13], v[204:205]
	v_pk_mul_f32 v[218:219], v[14:15], v[206:207]
	v_pk_add_f32 v[204:205], v[78:79], 1.0 op_sel_hi:[1,0]
	v_pk_add_f32 v[206:207], v[76:77], 1.0 op_sel_hi:[1,0]
	v_pk_fma_f32 v[218:219], v[204:205], v[218:219], v[74:75]
	v_pk_fma_f32 v[216:217], v[206:207], v[216:217], v[72:73]
	v_cmp_lt_i32_e32 vcc, v194, v226
	v_cvt_pk_bf16_f32 v216, v216, v217
	v_cvt_pk_bf16_f32 v217, v218, v219
	global_store_dwordx2 v[236:237], v[216:217], off offset:1536
	s_and_saveexec_b64 s[6:7], vcc
	s_cbranch_execz .LBB0_1167
	s_waitcnt vmcnt(43)
	v_lshlrev_b32_e32 v216, 16, v202
	v_and_b32_e32 v217, 0xffff0000, v202
	v_lshlrev_b32_e32 v202, 16, v203
	v_and_b32_e32 v203, 0xffff0000, v203
	v_pk_add_f32 v[126:127], v[126:127], v[202:203]
	s_waitcnt vmcnt(42)
	v_lshlrev_b32_e32 v202, 16, v200
	v_and_b32_e32 v203, 0xffff0000, v200
	v_lshlrev_b32_e32 v200, 16, v201
	v_and_b32_e32 v201, 0xffff0000, v201
	v_pk_add_f32 v[122:123], v[122:123], v[200:201]
	s_waitcnt vmcnt(41)
	v_lshlrev_b32_e32 v200, 16, v198
	v_and_b32_e32 v201, 0xffff0000, v198
	v_lshlrev_b32_e32 v198, 16, v199
	v_and_b32_e32 v199, 0xffff0000, v199
	v_ashrrev_i32_e32 v195, 31, v194
	v_pk_add_f32 v[124:125], v[124:125], v[216:217]
	v_pk_add_f32 v[118:119], v[118:119], v[198:199]
	s_waitcnt vmcnt(40)
	v_lshlrev_b32_e32 v198, 16, v196
	v_and_b32_e32 v199, 0xffff0000, v196
	v_lshlrev_b32_e32 v196, 16, v197
	v_and_b32_e32 v197, 0xffff0000, v197
	v_add_u32_e32 v129, 0xffffe001, v128
	v_lshlrev_b64 v[194:195], 11, v[194:195]
	v_pk_add_f32 v[120:121], v[120:121], v[202:203]
	v_pk_add_f32 v[114:115], v[114:115], v[196:197]
	v_pk_add_f32 v[112:113], v[112:113], v[198:199]
	v_ashrrev_i32_e32 v129, 10, v129
	v_lshl_add_u64 v[196:197], v[134:135], 0, v[194:195]
	v_cvt_pk_bf16_f32 v198, v124, v125
	v_cvt_pk_bf16_f32 v199, v126, v127
	v_pk_add_f32 v[116:117], v[116:117], v[200:201]
	v_add_u32_e32 v129, 1, v129
	v_cmp_lt_i32_e32 vcc, s29, v128
	global_store_dwordx2 v[196:197], v[198:199], off
	v_cvt_pk_bf16_f32 v198, v120, v121
	v_cvt_pk_bf16_f32 v199, v122, v123
	v_cndmask_b32_e32 v129, 0, v129, vcc
	global_store_dwordx2 v[196:197], v[198:199], off offset:512
	v_cvt_pk_bf16_f32 v198, v116, v117
	v_cvt_pk_bf16_f32 v199, v118, v119
	global_store_dwordx2 v[196:197], v[198:199], off offset:1024
	v_cvt_pk_bf16_f32 v198, v112, v113
	v_cvt_pk_bf16_f32 v199, v114, v115
	v_cmp_ne_u32_e32 vcc, v129, v235
	global_store_dwordx2 v[196:197], v[198:199], off offset:1536
	s_and_saveexec_b64 s[40:41], vcc
	s_cbranch_execz .LBB0_1153
	global_load_dwordx4 v[16:19], v[136:137], off
	global_load_dwordx4 v[20:23], v[138:139], off
	v_mad_i64_i32 v[196:197], s[42:43], v129, s16, v[152:153]
	s_mov_b64 s[42:43], 0

.LBB0_1153:
	s_or_b64 exec, exec, s[40:41]
	v_mov_b32_e32 v198, v125
	v_mov_b32_e32 v199, v121
	v_mov_b32_e32 v196, v124
	v_mov_b32_e32 v197, v120
	v_pk_mul_f32 v[198:199], v[198:199], v[198:199]
	v_mov_b32_e32 v200, v117
	v_pk_fma_f32 v[196:197], v[196:197], v[196:197], v[198:199]
	v_mov_b32_e32 v198, v126
	v_mov_b32_e32 v199, v122
	v_pk_fma_f32 v[196:197], v[198:199], v[198:199], v[196:197]
	v_mov_b32_e32 v198, v127
	v_mov_b32_e32 v199, v123
	v_mov_b32_e32 v201, v113
	v_pk_fma_f32 v[196:197], v[198:199], v[198:199], v[196:197]
	v_mov_b32_e32 v198, v116
	v_mov_b32_e32 v199, v112
	v_pk_mul_f32 v[200:201], v[200:201], v[200:201]
	v_add_f32_e32 v129, v196, v197
	v_pk_fma_f32 v[198:199], v[198:199], v[198:199], v[200:201]
	v_mov_b32_e32 v200, v118
	v_mov_b32_e32 v201, v114
	v_pk_fma_f32 v[198:199], v[200:201], v[200:201], v[198:199]
	v_mov_b32_e32 v200, v119
	v_mov_b32_e32 v201, v115
	v_pk_fma_f32 v[198:199], v[200:201], v[200:201], v[198:199]
	v_lshl_add_u64 v[194:195], v[132:133], 0, v[194:195]
	v_add_f32_e32 v129, v129, v198
	v_add_f32_e32 v129, v129, v199
	v_mov_b32_e32 v155, v129
	s_nop 1
	v_permlane32_swap_b32_e32 v155, v129
	s_nop 1
	v_add_f32_e32 v129, v129, v155
	v_mov_b32_e32 v155, v129
	s_nop 1
	v_permlane16_swap_b32_e32 v155, v129
	s_nop 1
	v_add_f32_e32 v129, v129, v155
	s_nop 1
	v_add_f32_dpp v129, v129, v129 row_ror:8 row_mask:0xf bank_mask:0xf
	s_nop 1
	v_add_f32_dpp v129, v129, v129 row_ror:4 row_mask:0xf bank_mask:0xf
	s_nop 1
	v_add_f32_dpp v129, v129, v129 quad_perm:[2,3,0,1] row_mask:0xf bank_mask:0xf
	s_nop 1
	v_add_f32_dpp v129, v129, v129 quad_perm:[1,0,3,2] row_mask:0xf bank_mask:0xf
	v_fmamk_f32 v129, v129, 0x3a800000, v234
	v_rsq_f32_e32 v129, v129
	s_nop 0
	v_mov_b32_e32 v196, v129
	v_pk_mul_f32 v[126:127], v[126:127], v[196:197] op_sel_hi:[1,0]
	v_pk_mul_f32 v[124:125], v[124:125], v[196:197] op_sel_hi:[1,0]
	v_pk_mul_f32 v[122:123], v[122:123], v[196:197] op_sel_hi:[1,0]
	v_pk_mul_f32 v[120:121], v[120:121], v[196:197] op_sel_hi:[1,0]
	v_pk_mul_f32 v[118:119], v[118:119], v[196:197] op_sel_hi:[1,0]
	v_pk_mul_f32 v[116:117], v[116:117], v[196:197] op_sel_hi:[1,0]
	v_pk_mul_f32 v[114:115], v[114:115], v[196:197] op_sel_hi:[1,0]
	v_pk_mul_f32 v[112:113], v[112:113], v[196:197] op_sel_hi:[1,0]
	v_pk_mul_f32 v[124:125], v[8:9], v[124:125]
	v_pk_mul_f32 v[126:127], v[10:11], v[126:127]
	v_pk_mul_f32 v[120:121], v[0:1], v[120:121]
	v_pk_mul_f32 v[122:123], v[2:3], v[122:123]
	v_pk_mul_f32 v[116:117], v[4:5], v[116:117]
	v_pk_mul_f32 v[118:119], v[6:7], v[118:119]
	v_pk_mul_f32 v[112:113], v[12:13], v[112:113]
	v_pk_mul_f32 v[114:115], v[14:15], v[114:115]
	v_pk_fma_f32 v[126:127], v[220:221], v[126:127], v[18:19]
	v_pk_fma_f32 v[124:125], v[222:223], v[124:125], v[16:17]
	v_pk_fma_f32 v[122:123], v[212:213], v[122:123], v[26:27]
	v_pk_fma_f32 v[120:121], v[214:215], v[120:121], v[24:25]
	v_pk_fma_f32 v[118:119], v[208:209], v[118:119], v[50:51]
	v_pk_fma_f32 v[116:117], v[210:211], v[116:117], v[48:49]
	v_pk_fma_f32 v[114:115], v[204:205], v[114:115], v[74:75]
	v_pk_fma_f32 v[112:113], v[206:207], v[112:113], v[72:73]
	v_cvt_pk_bf16_f32 v124, v124, v125
	v_cvt_pk_bf16_f32 v125, v126, v127
	v_cvt_pk_bf16_f32 v120, v120, v121
	v_cvt_pk_bf16_f32 v121, v122, v123
	v_cvt_pk_bf16_f32 v116, v116, v117
	v_cvt_pk_bf16_f32 v117, v118, v119
	v_cvt_pk_bf16_f32 v112, v112, v113
	v_cvt_pk_bf16_f32 v113, v114, v115
	global_store_dwordx2 v[194:195], v[124:125], off
	global_store_dwordx2 v[194:195], v[120:121], off offset:512
	global_store_dwordx2 v[194:195], v[116:117], off offset:1024
	global_store_dwordx2 v[194:195], v[112:113], off offset:1536
	s_or_b64 exec, exec, s[6:7]
	v_cmp_lt_i32_e32 vcc, v184, v226
	s_and_saveexec_b64 s[6:7], vcc
	s_cbranch_execnz .LBB0_1168

.LBB0_1165:
	s_or_b64 exec, exec, s[40:41]
	v_mov_b32_e32 v100, v93
	v_mov_b32_e32 v101, v89
	v_mov_b32_e32 v98, v92
	v_mov_b32_e32 v99, v88
	v_pk_mul_f32 v[100:101], v[100:101], v[100:101]
	v_mov_b32_e32 v102, v85
	v_pk_fma_f32 v[98:99], v[98:99], v[98:99], v[100:101]
	v_mov_b32_e32 v100, v94
	v_mov_b32_e32 v101, v90
	v_pk_fma_f32 v[98:99], v[100:101], v[100:101], v[98:99]
	v_mov_b32_e32 v100, v95
	v_mov_b32_e32 v101, v91
	v_mov_b32_e32 v103, v81
	v_pk_fma_f32 v[98:99], v[100:101], v[100:101], v[98:99]
	v_mov_b32_e32 v100, v84
	v_mov_b32_e32 v101, v80
	v_pk_mul_f32 v[102:103], v[102:103], v[102:103]
	v_add_f32_e32 v98, v98, v99
	v_pk_fma_f32 v[100:101], v[100:101], v[100:101], v[102:103]
	v_mov_b32_e32 v102, v86
	v_mov_b32_e32 v103, v82
	v_pk_fma_f32 v[100:101], v[102:103], v[102:103], v[100:101]
	v_mov_b32_e32 v102, v87
	v_mov_b32_e32 v103, v83
	v_pk_fma_f32 v[100:101], v[102:103], v[102:103], v[100:101]
	v_lshl_add_u64 v[96:97], v[132:133], 0, v[96:97]
	v_add_f32_e32 v98, v98, v100
	v_add_f32_e32 v98, v98, v101
	v_mov_b32_e32 v99, v98
	v_pk_add_f32 v[100:101], v[20:21], 1.0 op_sel_hi:[1,0]
	s_nop 1
	v_permlane32_swap_b32_e32 v99, v98
	s_nop 1
	v_add_f32_e32 v98, v98, v99
	v_mov_b32_e32 v99, v98
	s_nop 1
	v_permlane16_swap_b32_e32 v99, v98
	s_nop 1
	v_add_f32_e32 v98, v98, v99
	s_nop 1
	v_add_f32_dpp v98, v98, v98 row_ror:8 row_mask:0xf bank_mask:0xf
	s_nop 1
	v_add_f32_dpp v98, v98, v98 row_ror:4 row_mask:0xf bank_mask:0xf
	s_nop 1
	v_add_f32_dpp v98, v98, v98 quad_perm:[2,3,0,1] row_mask:0xf bank_mask:0xf
	s_nop 1
	v_add_f32_dpp v98, v98, v98 quad_perm:[1,0,3,2] row_mask:0xf bank_mask:0xf
	v_fmamk_f32 v98, v98, 0x3a800000, v234
	v_rsq_f32_e32 v102, v98
	v_pk_add_f32 v[98:99], v[22:23], 1.0 op_sel_hi:[1,0]
	v_pk_mul_f32 v[94:95], v[94:95], v[102:103] op_sel_hi:[1,0]
	v_pk_mul_f32 v[92:93], v[92:93], v[102:103] op_sel_hi:[1,0]
	v_pk_mul_f32 v[94:95], v[10:11], v[94:95]
	v_pk_mul_f32 v[92:93], v[8:9], v[92:93]
	v_pk_fma_f32 v[94:95], v[98:99], v[94:95], v[18:19]
	v_pk_fma_f32 v[92:93], v[100:101], v[92:93], v[16:17]
	v_pk_mul_f32 v[90:91], v[90:91], v[102:103] op_sel_hi:[1,0]
	v_cvt_pk_bf16_f32 v92, v92, v93
	v_cvt_pk_bf16_f32 v93, v94, v95
	v_pk_mul_f32 v[88:89], v[88:89], v[102:103] op_sel_hi:[1,0]
	global_store_dwordx2 v[96:97], v[92:93], off
	v_pk_mul_f32 v[88:89], v[0:1], v[88:89]
	v_pk_mul_f32 v[90:91], v[2:3], v[90:91]
	v_pk_add_f32 v[92:93], v[30:31], 1.0 op_sel_hi:[1,0]
	v_pk_add_f32 v[94:95], v[28:29], 1.0 op_sel_hi:[1,0]
	v_pk_fma_f32 v[90:91], v[92:93], v[90:91], v[26:27]
	v_pk_fma_f32 v[88:89], v[94:95], v[88:89], v[24:25]
	v_pk_mul_f32 v[86:87], v[86:87], v[102:103] op_sel_hi:[1,0]
	v_cvt_pk_bf16_f32 v88, v88, v89
	v_cvt_pk_bf16_f32 v89, v90, v91
	v_pk_mul_f32 v[84:85], v[84:85], v[102:103] op_sel_hi:[1,0]
	global_store_dwordx2 v[96:97], v[88:89], off offset:512
	v_pk_mul_f32 v[84:85], v[4:5], v[84:85]
	v_pk_mul_f32 v[86:87], v[6:7], v[86:87]
	v_pk_add_f32 v[88:89], v[54:55], 1.0 op_sel_hi:[1,0]
	v_pk_add_f32 v[90:91], v[52:53], 1.0 op_sel_hi:[1,0]
	v_pk_fma_f32 v[86:87], v[88:89], v[86:87], v[50:51]
	v_pk_fma_f32 v[84:85], v[90:91], v[84:85], v[48:49]
	v_pk_mul_f32 v[82:83], v[82:83], v[102:103] op_sel_hi:[1,0]
	v_cvt_pk_bf16_f32 v84, v84, v85
	v_cvt_pk_bf16_f32 v85, v86, v87
	v_pk_mul_f32 v[80:81], v[80:81], v[102:103] op_sel_hi:[1,0]
	global_store_dwordx2 v[96:97], v[84:85], off offset:1024
	v_pk_mul_f32 v[80:81], v[12:13], v[80:81]
	v_pk_mul_f32 v[82:83], v[14:15], v[82:83]
	v_pk_add_f32 v[84:85], v[78:79], 1.0 op_sel_hi:[1,0]
	v_pk_add_f32 v[86:87], v[76:77], 1.0 op_sel_hi:[1,0]
	v_pk_fma_f32 v[82:83], v[84:85], v[82:83], v[74:75]
	v_pk_fma_f32 v[80:81], v[86:87], v[80:81], v[72:73]
	s_nop 0
	v_cvt_pk_bf16_f32 v80, v80, v81
	v_cvt_pk_bf16_f32 v81, v82, v83
	global_store_dwordx2 v[96:97], v[80:81], off offset:1536
	s_or_b64 exec, exec, s[6:7]
	v_cmp_lt_i32_e32 vcc, v164, v226
	s_and_saveexec_b64 s[6:7], vcc
	s_cbranch_execnz .LBB0_1180

.LBB0_1178:
	s_or_b64 exec, exec, s[40:41]
	v_mov_b32_e32 v116, v109
	v_mov_b32_e32 v117, v105
	v_mov_b32_e32 v114, v108
	v_mov_b32_e32 v115, v104
	v_pk_mul_f32 v[116:117], v[116:117], v[116:117]
	v_mov_b32_e32 v118, v101
	v_pk_fma_f32 v[114:115], v[114:115], v[114:115], v[116:117]
	v_mov_b32_e32 v116, v110
	v_mov_b32_e32 v117, v106
	v_pk_fma_f32 v[114:115], v[116:117], v[116:117], v[114:115]
	v_mov_b32_e32 v116, v111
	v_mov_b32_e32 v117, v107
	v_mov_b32_e32 v119, v97
	v_pk_fma_f32 v[114:115], v[116:117], v[116:117], v[114:115]
	v_mov_b32_e32 v116, v100
	v_mov_b32_e32 v117, v96
	v_pk_mul_f32 v[118:119], v[118:119], v[118:119]
	v_add_f32_e32 v114, v114, v115
	v_pk_fma_f32 v[116:117], v[116:117], v[116:117], v[118:119]
	v_mov_b32_e32 v118, v102
	v_mov_b32_e32 v119, v98
	v_pk_fma_f32 v[116:117], v[118:119], v[118:119], v[116:117]
	v_mov_b32_e32 v118, v103
	v_mov_b32_e32 v119, v99
	v_pk_fma_f32 v[116:117], v[118:119], v[118:119], v[116:117]
	v_lshl_add_u64 v[112:113], v[132:133], 0, v[112:113]
	v_add_f32_e32 v114, v114, v116
	v_add_f32_e32 v114, v114, v117
	v_mov_b32_e32 v115, v114
	v_pk_add_f32 v[116:117], v[20:21], 1.0 op_sel_hi:[1,0]
	s_nop 1
	v_permlane32_swap_b32_e32 v115, v114
	s_nop 1
	v_add_f32_e32 v114, v114, v115
	v_mov_b32_e32 v115, v114
	s_nop 1
	v_permlane16_swap_b32_e32 v115, v114
	s_nop 1
	v_add_f32_e32 v114, v114, v115
	s_nop 1
	v_add_f32_dpp v114, v114, v114 row_ror:8 row_mask:0xf bank_mask:0xf
	s_nop 1
	v_add_f32_dpp v114, v114, v114 row_ror:4 row_mask:0xf bank_mask:0xf
	s_nop 1
	v_add_f32_dpp v114, v114, v114 quad_perm:[2,3,0,1] row_mask:0xf bank_mask:0xf
	s_nop 1
	v_add_f32_dpp v114, v114, v114 quad_perm:[1,0,3,2] row_mask:0xf bank_mask:0xf
	v_fmamk_f32 v114, v114, 0x3a800000, v234
	v_rsq_f32_e32 v118, v114
	v_pk_add_f32 v[114:115], v[22:23], 1.0 op_sel_hi:[1,0]
	v_pk_mul_f32 v[110:111], v[110:111], v[118:119] op_sel_hi:[1,0]
	v_pk_mul_f32 v[108:109], v[108:109], v[118:119] op_sel_hi:[1,0]
	v_pk_mul_f32 v[110:111], v[10:11], v[110:111]
	v_pk_mul_f32 v[108:109], v[8:9], v[108:109]
	v_pk_fma_f32 v[110:111], v[114:115], v[110:111], v[18:19]
	v_pk_fma_f32 v[108:109], v[116:117], v[108:109], v[16:17]
	v_pk_mul_f32 v[106:107], v[106:107], v[118:119] op_sel_hi:[1,0]
	v_cvt_pk_bf16_f32 v108, v108, v109
	v_cvt_pk_bf16_f32 v109, v110, v111
	v_pk_mul_f32 v[104:105], v[104:105], v[118:119] op_sel_hi:[1,0]
	global_store_dwordx2 v[112:113], v[108:109], off
	v_pk_mul_f32 v[104:105], v[0:1], v[104:105]
	v_pk_mul_f32 v[106:107], v[2:3], v[106:107]
	v_pk_add_f32 v[108:109], v[30:31], 1.0 op_sel_hi:[1,0]
	v_pk_add_f32 v[110:111], v[28:29], 1.0 op_sel_hi:[1,0]
	v_pk_fma_f32 v[106:107], v[108:109], v[106:107], v[26:27]
	v_pk_fma_f32 v[104:105], v[110:111], v[104:105], v[24:25]
	v_pk_mul_f32 v[102:103], v[102:103], v[118:119] op_sel_hi:[1,0]
	v_cvt_pk_bf16_f32 v104, v104, v105
	v_cvt_pk_bf16_f32 v105, v106, v107
	v_pk_mul_f32 v[100:101], v[100:101], v[118:119] op_sel_hi:[1,0]
	global_store_dwordx2 v[112:113], v[104:105], off offset:512
	v_pk_mul_f32 v[100:101], v[4:5], v[100:101]
	v_pk_mul_f32 v[102:103], v[6:7], v[102:103]
	v_pk_add_f32 v[104:105], v[54:55], 1.0 op_sel_hi:[1,0]
	v_pk_add_f32 v[106:107], v[52:53], 1.0 op_sel_hi:[1,0]
	v_pk_fma_f32 v[102:103], v[104:105], v[102:103], v[50:51]
	v_pk_fma_f32 v[100:101], v[106:107], v[100:101], v[48:49]
	v_pk_mul_f32 v[98:99], v[98:99], v[118:119] op_sel_hi:[1,0]
	v_cvt_pk_bf16_f32 v100, v100, v101
	v_cvt_pk_bf16_f32 v101, v102, v103
	v_pk_mul_f32 v[96:97], v[96:97], v[118:119] op_sel_hi:[1,0]
	global_store_dwordx2 v[112:113], v[100:101], off offset:1024
	v_pk_mul_f32 v[96:97], v[12:13], v[96:97]
	v_pk_mul_f32 v[98:99], v[14:15], v[98:99]
	v_pk_add_f32 v[100:101], v[78:79], 1.0 op_sel_hi:[1,0]
	v_pk_add_f32 v[102:103], v[76:77], 1.0 op_sel_hi:[1,0]
	v_pk_fma_f32 v[98:99], v[100:101], v[98:99], v[74:75]
	v_pk_fma_f32 v[96:97], v[102:103], v[96:97], v[72:73]
	s_nop 0
	v_cvt_pk_bf16_f32 v96, v96, v97
	v_cvt_pk_bf16_f32 v97, v98, v99
	global_store_dwordx2 v[112:113], v[96:97], off offset:1536
	s_or_b64 exec, exec, s[6:7]
	v_cmp_lt_i32_e32 vcc, v174, v226
	s_and_saveexec_b64 s[6:7], vcc
	s_cbranch_execnz .LBB0_1155

.LBB0_1190:
	s_or_b64 exec, exec, s[40:41]
	v_mov_b32_e32 v84, v69
	v_mov_b32_e32 v85, v65
	v_mov_b32_e32 v82, v68
	v_mov_b32_e32 v83, v64
	v_pk_mul_f32 v[84:85], v[84:85], v[84:85]
	v_mov_b32_e32 v86, v61
	v_pk_fma_f32 v[82:83], v[82:83], v[82:83], v[84:85]
	v_mov_b32_e32 v84, v70
	v_mov_b32_e32 v85, v66
	v_pk_fma_f32 v[82:83], v[84:85], v[84:85], v[82:83]
	v_mov_b32_e32 v84, v71
	v_mov_b32_e32 v85, v67
	v_mov_b32_e32 v87, v57
	v_pk_fma_f32 v[82:83], v[84:85], v[84:85], v[82:83]
	v_mov_b32_e32 v84, v60
	v_mov_b32_e32 v85, v56
	v_pk_mul_f32 v[86:87], v[86:87], v[86:87]
	v_add_f32_e32 v82, v82, v83
	v_pk_fma_f32 v[84:85], v[84:85], v[84:85], v[86:87]
	v_mov_b32_e32 v86, v62
	v_mov_b32_e32 v87, v58
	v_pk_fma_f32 v[84:85], v[86:87], v[86:87], v[84:85]
	v_mov_b32_e32 v86, v63
	v_mov_b32_e32 v87, v59
	v_pk_fma_f32 v[84:85], v[86:87], v[86:87], v[84:85]
	v_lshl_add_u64 v[80:81], v[132:133], 0, v[80:81]
	v_add_f32_e32 v82, v82, v84
	v_add_f32_e32 v82, v82, v85
	v_mov_b32_e32 v83, v82
	v_pk_add_f32 v[84:85], v[20:21], 1.0 op_sel_hi:[1,0]
	s_nop 1
	v_permlane32_swap_b32_e32 v83, v82
	s_nop 1
	v_add_f32_e32 v82, v82, v83
	v_mov_b32_e32 v83, v82
	s_nop 1
	v_permlane16_swap_b32_e32 v83, v82
	s_nop 1
	v_add_f32_e32 v82, v82, v83
	s_nop 1
	v_add_f32_dpp v82, v82, v82 row_ror:8 row_mask:0xf bank_mask:0xf
	s_nop 1
	v_add_f32_dpp v82, v82, v82 row_ror:4 row_mask:0xf bank_mask:0xf
	s_nop 1
	v_add_f32_dpp v82, v82, v82 quad_perm:[2,3,0,1] row_mask:0xf bank_mask:0xf
	s_nop 1
	v_add_f32_dpp v82, v82, v82 quad_perm:[1,0,3,2] row_mask:0xf bank_mask:0xf
	v_fmamk_f32 v82, v82, 0x3a800000, v234
	v_rsq_f32_e32 v86, v82
	v_pk_add_f32 v[82:83], v[22:23], 1.0 op_sel_hi:[1,0]
	v_pk_mul_f32 v[70:71], v[70:71], v[86:87] op_sel_hi:[1,0]
	v_pk_mul_f32 v[68:69], v[68:69], v[86:87] op_sel_hi:[1,0]
	v_pk_mul_f32 v[70:71], v[10:11], v[70:71]
	v_pk_mul_f32 v[68:69], v[8:9], v[68:69]
	v_pk_fma_f32 v[70:71], v[82:83], v[70:71], v[18:19]
	v_pk_fma_f32 v[68:69], v[84:85], v[68:69], v[16:17]
	v_pk_mul_f32 v[66:67], v[66:67], v[86:87] op_sel_hi:[1,0]
	v_cvt_pk_bf16_f32 v68, v68, v69
	v_cvt_pk_bf16_f32 v69, v70, v71
	v_pk_mul_f32 v[64:65], v[64:65], v[86:87] op_sel_hi:[1,0]
	global_store_dwordx2 v[80:81], v[68:69], off
	v_pk_mul_f32 v[64:65], v[0:1], v[64:65]
	v_pk_mul_f32 v[66:67], v[2:3], v[66:67]
	v_pk_add_f32 v[68:69], v[30:31], 1.0 op_sel_hi:[1,0]
	v_pk_add_f32 v[70:71], v[28:29], 1.0 op_sel_hi:[1,0]
	v_pk_fma_f32 v[66:67], v[68:69], v[66:67], v[26:27]
	v_pk_fma_f32 v[64:65], v[70:71], v[64:65], v[24:25]
	v_pk_mul_f32 v[62:63], v[62:63], v[86:87] op_sel_hi:[1,0]
	v_cvt_pk_bf16_f32 v64, v64, v65
	v_cvt_pk_bf16_f32 v65, v66, v67
	v_pk_mul_f32 v[60:61], v[60:61], v[86:87] op_sel_hi:[1,0]
	global_store_dwordx2 v[80:81], v[64:65], off offset:512
	v_pk_mul_f32 v[60:61], v[4:5], v[60:61]
	v_pk_mul_f32 v[62:63], v[6:7], v[62:63]
	v_pk_add_f32 v[64:65], v[54:55], 1.0 op_sel_hi:[1,0]
	v_pk_add_f32 v[66:67], v[52:53], 1.0 op_sel_hi:[1,0]
	v_pk_fma_f32 v[62:63], v[64:65], v[62:63], v[50:51]
	v_pk_fma_f32 v[60:61], v[66:67], v[60:61], v[48:49]
	v_pk_mul_f32 v[58:59], v[58:59], v[86:87] op_sel_hi:[1,0]
	v_cvt_pk_bf16_f32 v60, v60, v61
	v_cvt_pk_bf16_f32 v61, v62, v63
	v_pk_mul_f32 v[56:57], v[56:57], v[86:87] op_sel_hi:[1,0]
	global_store_dwordx2 v[80:81], v[60:61], off offset:1024
	v_pk_mul_f32 v[56:57], v[12:13], v[56:57]
	v_pk_mul_f32 v[58:59], v[14:15], v[58:59]
	v_pk_add_f32 v[60:61], v[78:79], 1.0 op_sel_hi:[1,0]
	v_pk_add_f32 v[62:63], v[76:77], 1.0 op_sel_hi:[1,0]
	v_pk_fma_f32 v[58:59], v[60:61], v[58:59], v[74:75]
	v_pk_fma_f32 v[56:57], v[62:63], v[56:57], v[72:73]
	s_nop 0
	v_cvt_pk_bf16_f32 v56, v56, v57
	v_cvt_pk_bf16_f32 v57, v58, v59
	global_store_dwordx2 v[80:81], v[56:57], off offset:1536
	s_or_b64 exec, exec, s[6:7]
	v_cmp_lt_i32_e32 vcc, v154, v226
	s_and_saveexec_b64 s[6:7], vcc
	s_cbranch_execz .LBB0_1131

.LBB0_1559:
	v_add_u32_e32 v35, s90, v128
	s_waitcnt vmcnt(6)
	v_add_co_u32_e32 v36, vcc, s10, v24
	s_waitcnt vmcnt(4)
	v_min_i32_e32 v38, 0x2fff, v35
	v_addc_co_u32_e32 v37, vcc, -1, v25, vcc
	global_load_dwordx2 v[130:131], v[24:25], off
	global_load_dwordx2 v[132:133], v[36:37], off
	v_ashrrev_i32_e32 v39, 31, v38
	v_lshlrev_b64 v[38:39], 11, v[38:39]
	v_lshl_add_u64 v[40:41], v[16:17], 0, v[38:39]
	v_lshl_add_u64 v[38:39], v[18:19], 0, v[38:39]
	global_load_dwordx2 v[134:135], v[24:25], off offset:-512
	global_load_dwordx2 v[136:137], v[36:37], off offset:-512
	global_load_dwordx2 v[106:107], v[40:41], off
	global_load_dwordx2 v[110:111], v[40:41], off offset:512
	global_load_dwordx2 v[114:115], v[40:41], off offset:1024
	global_load_dwordx2 v[118:119], v[40:41], off offset:1536
	global_load_dwordx2 v[108:109], v[38:39], off
	global_load_dwordx2 v[112:113], v[38:39], off offset:512
	global_load_dwordx2 v[116:117], v[38:39], off offset:1024
	global_load_dwordx2 v[120:121], v[38:39], off offset:1536
	global_load_dwordx2 v[138:139], v[24:25], off offset:-1024
	global_load_dwordx2 v[140:141], v[36:37], off offset:-1024
	v_add_u32_e32 v88, s90, v129
	v_min_i32_e32 v38, 0x2fff, v88
	v_ashrrev_i32_e32 v39, 31, v38
	v_lshlrev_b64 v[38:39], 11, v[38:39]
	v_lshl_add_u64 v[40:41], v[16:17], 0, v[38:39]
	v_lshl_add_u64 v[38:39], v[18:19], 0, v[38:39]
	global_load_dwordx2 v[142:143], v[24:25], off offset:-1536
	global_load_dwordx2 v[102:103], v[40:41], off
	global_load_dwordx2 v[98:99], v[40:41], off offset:512
	global_load_dwordx2 v[94:95], v[40:41], off offset:1024
	global_load_dwordx2 v[90:91], v[40:41], off offset:1536
	global_load_dwordx2 v[144:145], v[36:37], off offset:-1536
	global_load_dwordx2 v[104:105], v[38:39], off
	global_load_dwordx2 v[100:101], v[38:39], off offset:512
	global_load_dwordx2 v[96:97], v[38:39], off offset:1024
	global_load_dwordx2 v[92:93], v[38:39], off offset:1536
	v_add_u32_e32 v70, s90, v30
	v_min_i32_e32 v36, 0x2fff, v70
	v_ashrrev_i32_e32 v37, 31, v36
	v_lshlrev_b64 v[36:37], 11, v[36:37]
	v_lshl_add_u64 v[38:39], v[16:17], 0, v[36:37]
	v_lshl_add_u64 v[36:37], v[18:19], 0, v[36:37]
	v_add_u32_e32 v52, s90, v29
	global_load_dwordx2 v[84:85], v[38:39], off
	global_load_dwordx2 v[80:81], v[38:39], off offset:512
	global_load_dwordx2 v[76:77], v[38:39], off offset:1024
	global_load_dwordx2 v[72:73], v[38:39], off offset:1536
	global_load_dwordx2 v[86:87], v[36:37], off
	global_load_dwordx2 v[82:83], v[36:37], off offset:512
	global_load_dwordx2 v[78:79], v[36:37], off offset:1024
	global_load_dwordx2 v[74:75], v[36:37], off offset:1536
	v_min_i32_e32 v36, 0x2fff, v52
	v_ashrrev_i32_e32 v37, 31, v36
	v_lshlrev_b64 v[36:37], 11, v[36:37]
	v_lshl_add_u64 v[38:39], v[16:17], 0, v[36:37]
	v_lshl_add_u64 v[36:37], v[18:19], 0, v[36:37]
	v_add_u32_e32 v34, s90, v28
	global_load_dwordx2 v[66:67], v[38:39], off
	global_load_dwordx2 v[62:63], v[38:39], off offset:512
	global_load_dwordx2 v[58:59], v[38:39], off offset:1024
	global_load_dwordx2 v[54:55], v[38:39], off offset:1536
	global_load_dwordx2 v[68:69], v[36:37], off
	global_load_dwordx2 v[64:65], v[36:37], off offset:512
	global_load_dwordx2 v[60:61], v[36:37], off offset:1024
	global_load_dwordx2 v[56:57], v[36:37], off offset:1536
	v_min_i32_e32 v36, 0x2fff, v34
	v_ashrrev_i32_e32 v37, 31, v36
	v_lshlrev_b64 v[36:37], 11, v[36:37]
	v_lshl_add_u64 v[38:39], v[16:17], 0, v[36:37]
	v_lshl_add_u64 v[146:147], v[18:19], 0, v[36:37]
	global_load_dwordx2 v[48:49], v[38:39], off
	global_load_dwordx2 v[44:45], v[38:39], off offset:512
	global_load_dwordx2 v[40:41], v[38:39], off offset:1024
	global_load_dwordx2 v[36:37], v[38:39], off offset:1536
	global_load_dwordx2 v[50:51], v[146:147], off
	global_load_dwordx2 v[46:47], v[146:147], off offset:512
	global_load_dwordx2 v[42:43], v[146:147], off offset:1024
	s_nop 0
	global_load_dwordx2 v[38:39], v[146:147], off offset:1536
	s_waitcnt vmcnt(47)
	v_lshlrev_b32_e32 v146, 16, v130
	v_and_b32_e32 v147, 0xffff0000, v130
	v_lshlrev_b32_e32 v130, 16, v131
	v_and_b32_e32 v131, 0xffff0000, v131
	s_waitcnt vmcnt(46)
	v_lshlrev_b32_e32 v148, 16, v132
	v_and_b32_e32 v149, 0xffff0000, v132
	v_lshlrev_b32_e32 v132, 16, v133
	v_and_b32_e32 v133, 0xffff0000, v133
	v_pk_add_f32 v[150:151], v[130:131], v[132:133]
	s_waitcnt vmcnt(45)
	v_lshlrev_b32_e32 v130, 16, v134
	v_and_b32_e32 v131, 0xffff0000, v134
	v_lshlrev_b32_e32 v132, 16, v135
	v_and_b32_e32 v133, 0xffff0000, v135
	s_waitcnt vmcnt(44)
	v_lshlrev_b32_e32 v134, 16, v136
	v_and_b32_e32 v135, 0xffff0000, v136
	v_lshlrev_b32_e32 v136, 16, v137
	v_and_b32_e32 v137, 0xffff0000, v137
	v_pk_add_f32 v[136:137], v[132:133], v[136:137]
	v_pk_add_f32 v[134:135], v[130:131], v[134:135]
	s_waitcnt vmcnt(35)
	v_lshlrev_b32_e32 v130, 16, v138
	v_and_b32_e32 v131, 0xffff0000, v138
	v_lshlrev_b32_e32 v132, 16, v139
	v_and_b32_e32 v133, 0xffff0000, v139
	s_waitcnt vmcnt(34)
	v_lshlrev_b32_e32 v138, 16, v140
	v_and_b32_e32 v139, 0xffff0000, v140
	v_lshlrev_b32_e32 v140, 16, v141
	v_and_b32_e32 v141, 0xffff0000, v141
	v_pk_add_f32 v[140:141], v[132:133], v[140:141]
	v_pk_add_f32 v[138:139], v[130:131], v[138:139]
	s_waitcnt vmcnt(33)
	v_lshlrev_b32_e32 v130, 16, v142
	v_and_b32_e32 v131, 0xffff0000, v142
	v_lshlrev_b32_e32 v132, 16, v143
	v_and_b32_e32 v133, 0xffff0000, v143
	s_waitcnt vmcnt(28)
	v_lshlrev_b32_e32 v142, 16, v144
	v_and_b32_e32 v143, 0xffff0000, v144
	v_lshlrev_b32_e32 v144, 16, v145
	v_and_b32_e32 v145, 0xffff0000, v145
	v_pk_add_f32 v[130:131], v[130:131], v[142:143]
	v_pk_add_f32 v[132:133], v[132:133], v[144:145]
	v_mov_b32_e32 v144, v139
	v_mov_b32_e32 v145, v131
	v_mov_b32_e32 v142, v138
	v_mov_b32_e32 v143, v130
	v_pk_mul_f32 v[144:145], v[144:145], v[144:145]
	v_pk_add_f32 v[146:147], v[146:147], v[148:149]
	v_pk_fma_f32 v[142:143], v[142:143], v[142:143], v[144:145]
	v_mov_b32_e32 v144, v140
	v_mov_b32_e32 v145, v132
	v_pk_fma_f32 v[142:143], v[144:145], v[144:145], v[142:143]
	v_mov_b32_e32 v144, v141
	v_mov_b32_e32 v145, v133
	v_mov_b32_e32 v148, v147
	v_mov_b32_e32 v149, v135
	v_pk_fma_f32 v[142:143], v[144:145], v[144:145], v[142:143]
	v_mov_b32_e32 v144, v146
	v_mov_b32_e32 v145, v134
	v_pk_mul_f32 v[148:149], v[148:149], v[148:149]
	v_add_f32_e32 v53, v142, v143
	v_pk_fma_f32 v[144:145], v[144:145], v[144:145], v[148:149]
	v_mov_b32_e32 v148, v150
	v_mov_b32_e32 v149, v136
	v_pk_fma_f32 v[144:145], v[148:149], v[148:149], v[144:145]
	v_mov_b32_e32 v148, v151
	v_mov_b32_e32 v149, v137
	v_pk_fma_f32 v[144:145], v[148:149], v[148:149], v[144:145]
	s_nop 0
	v_add_f32_e32 v53, v145, v53
	v_add_f32_e32 v53, v144, v53
	v_mov_b32_e32 v71, v53
	v_lshl_add_u64 v[144:145], v[32:33], 0, v[22:23]
	s_nop 1
	v_permlane32_swap_b32_e32 v71, v53
	s_nop 1
	v_add_f32_e32 v53, v53, v71
	v_mov_b32_e32 v71, v53
	s_nop 1
	v_permlane16_swap_b32_e32 v71, v53
	s_nop 1
	v_add_f32_e32 v53, v53, v71
	s_nop 1
	v_add_f32_dpp v53, v53, v53 row_ror:8 row_mask:0xf bank_mask:0xf
	s_nop 1
	v_add_f32_dpp v53, v53, v53 row_ror:4 row_mask:0xf bank_mask:0xf
	s_nop 1
	v_add_f32_dpp v53, v53, v53 quad_perm:[2,3,0,1] row_mask:0xf bank_mask:0xf
	s_nop 1
	v_add_f32_dpp v53, v53, v53 quad_perm:[1,0,3,2] row_mask:0xf bank_mask:0xf
	v_fmamk_f32 v53, v53, 0x3a800000, v31
	v_rsq_f32_e32 v53, v53
	s_nop 0
	v_mov_b32_e32 v142, v53
	v_pk_mul_f32 v[130:131], v[130:131], v[142:143] op_sel_hi:[1,0]
	v_pk_mul_f32 v[132:133], v[132:133], v[142:143] op_sel_hi:[1,0]
	v_pk_mul_f32 v[130:131], v[0:1], v[130:131]
	v_pk_mul_f32 v[132:133], v[2:3], v[132:133]
	global_store_dwordx4 v[144:145], v[130:133], off nt
	v_cmp_gt_i32_e32 vcc, s8, v35
	s_nop 0
	v_pk_mul_f32 v[130:131], v[138:139], v[142:143] op_sel_hi:[1,0]
	v_pk_mul_f32 v[132:133], v[140:141], v[142:143] op_sel_hi:[1,0]
	v_pk_mul_f32 v[130:131], v[4:5], v[130:131]
	v_pk_mul_f32 v[132:133], v[6:7], v[132:133]
	global_store_dwordx4 v[144:145], v[130:133], off offset:1024 nt
	s_nop 1
	v_pk_mul_f32 v[130:131], v[134:135], v[142:143] op_sel_hi:[1,0]
	v_pk_mul_f32 v[132:133], v[136:137], v[142:143] op_sel_hi:[1,0]
	v_pk_mul_f32 v[130:131], v[8:9], v[130:131]
	v_pk_mul_f32 v[132:133], v[10:11], v[132:133]
	global_store_dwordx4 v[144:145], v[130:133], off offset:2048 nt
	s_nop 1
	v_pk_mul_f32 v[130:131], v[146:147], v[142:143] op_sel_hi:[1,0]
	v_pk_mul_f32 v[132:133], v[150:151], v[142:143] op_sel_hi:[1,0]
	v_pk_mul_f32 v[130:131], v[12:13], v[130:131]
	v_pk_mul_f32 v[132:133], v[14:15], v[132:133]
	global_store_dwordx4 v[144:145], v[130:133], off offset:3072 nt
	s_and_saveexec_b64 s[6:7], vcc
	s_cbranch_execz .LBB0_1561
	v_lshlrev_b32_e32 v130, 16, v118
	v_and_b32_e32 v131, 0xffff0000, v118
	v_lshlrev_b32_e32 v118, 16, v119
	v_and_b32_e32 v119, 0xffff0000, v119
	v_lshlrev_b32_e32 v132, 16, v120
	v_and_b32_e32 v133, 0xffff0000, v120
	v_lshlrev_b32_e32 v120, 16, v121
	v_and_b32_e32 v121, 0xffff0000, v121
	v_pk_add_f32 v[118:119], v[118:119], v[120:121]
	v_pk_add_f32 v[120:121], v[130:131], v[132:133]
	v_lshlrev_b32_e32 v130, 16, v114
	v_and_b32_e32 v131, 0xffff0000, v114
	v_lshlrev_b32_e32 v114, 16, v115
	v_and_b32_e32 v115, 0xffff0000, v115
	v_lshlrev_b32_e32 v132, 16, v116
	v_and_b32_e32 v133, 0xffff0000, v116
	v_lshlrev_b32_e32 v116, 16, v117
	v_and_b32_e32 v117, 0xffff0000, v117
	v_pk_add_f32 v[114:115], v[114:115], v[116:117]
	v_pk_add_f32 v[116:117], v[130:131], v[132:133]
	v_lshlrev_b32_e32 v130, 16, v110
	v_and_b32_e32 v131, 0xffff0000, v110
	v_lshlrev_b32_e32 v110, 16, v111
	v_and_b32_e32 v111, 0xffff0000, v111
	v_lshlrev_b32_e32 v132, 16, v112
	v_and_b32_e32 v133, 0xffff0000, v112
	v_lshlrev_b32_e32 v112, 16, v113
	v_and_b32_e32 v113, 0xffff0000, v113
	v_pk_add_f32 v[110:111], v[110:111], v[112:113]
	v_pk_add_f32 v[112:113], v[130:131], v[132:133]
	v_lshlrev_b32_e32 v130, 16, v106
	v_and_b32_e32 v131, 0xffff0000, v106
	v_lshlrev_b32_e32 v106, 16, v107
	v_and_b32_e32 v107, 0xffff0000, v107
	v_lshlrev_b32_e32 v132, 16, v108
	v_and_b32_e32 v133, 0xffff0000, v108
	v_lshlrev_b32_e32 v108, 16, v109
	v_and_b32_e32 v109, 0xffff0000, v109
	v_pk_add_f32 v[106:107], v[106:107], v[108:109]
	v_pk_add_f32 v[108:109], v[130:131], v[132:133]
	v_mov_b32_e32 v133, v113
	v_mov_b32_e32 v132, v109
	v_mov_b32_e32 v130, v108
	v_mov_b32_e32 v131, v112
	v_pk_mul_f32 v[132:133], v[132:133], v[132:133]
	v_mov_b32_e32 v134, v117
	v_pk_fma_f32 v[130:131], v[130:131], v[130:131], v[132:133]
	v_mov_b32_e32 v132, v106
	v_mov_b32_e32 v133, v110
	v_pk_fma_f32 v[130:131], v[132:133], v[132:133], v[130:131]
	v_mov_b32_e32 v132, v107
	v_mov_b32_e32 v133, v111
	v_mov_b32_e32 v135, v121
	v_pk_fma_f32 v[130:131], v[132:133], v[132:133], v[130:131]
	v_mov_b32_e32 v132, v116
	v_mov_b32_e32 v133, v120
	v_pk_mul_f32 v[134:135], v[134:135], v[134:135]
	v_add_f32_e32 v53, v130, v131
	v_pk_fma_f32 v[132:133], v[132:133], v[132:133], v[134:135]
	v_mov_b32_e32 v134, v114
	v_mov_b32_e32 v135, v118
	v_pk_fma_f32 v[132:133], v[134:135], v[134:135], v[132:133]
	v_mov_b32_e32 v134, v115
	v_mov_b32_e32 v135, v119
	v_pk_fma_f32 v[132:133], v[134:135], v[134:135], v[132:133]
	s_nop 0
	v_add_f32_e32 v53, v53, v132
	v_add_f32_e32 v53, v53, v133
	v_mov_b32_e32 v71, v53
	v_lshl_add_u64 v[132:133], v[32:33], 0, v[26:27]
	s_nop 1
	v_permlane32_swap_b32_e32 v71, v53
	s_nop 1
	v_add_f32_e32 v53, v53, v71
	v_mov_b32_e32 v71, v53
	s_nop 1
	v_permlane16_swap_b32_e32 v71, v53
	s_nop 1
	v_add_f32_e32 v53, v53, v71
	s_nop 1
	v_add_f32_dpp v53, v53, v53 row_ror:8 row_mask:0xf bank_mask:0xf
	s_nop 1
	v_add_f32_dpp v53, v53, v53 row_ror:4 row_mask:0xf bank_mask:0xf
	s_nop 1
	v_add_f32_dpp v53, v53, v53 quad_perm:[2,3,0,1] row_mask:0xf bank_mask:0xf
	s_nop 1
	v_add_f32_dpp v53, v53, v53 quad_perm:[1,0,3,2] row_mask:0xf bank_mask:0xf
	v_fmamk_f32 v53, v53, 0x3a800000, v31
	v_rsq_f32_e32 v53, v53
	s_nop 0
	v_mov_b32_e32 v130, v53
	v_pk_mul_f32 v[134:135], v[108:109], v[130:131] op_sel_hi:[1,0]
	v_pk_mul_f32 v[106:107], v[106:107], v[130:131] op_sel_hi:[1,0]
	s_nop 0
	v_pk_mul_f32 v[108:109], v[2:3], v[106:107]
	v_pk_mul_f32 v[106:107], v[0:1], v[134:135]
	global_store_dwordx4 v[132:133], v[106:109], off nt
	s_nop 1
	v_pk_mul_f32 v[106:107], v[112:113], v[130:131] op_sel_hi:[1,0]
	v_pk_mul_f32 v[108:109], v[110:111], v[130:131] op_sel_hi:[1,0]
	v_pk_mul_f32 v[106:107], v[4:5], v[106:107]
	v_pk_mul_f32 v[108:109], v[6:7], v[108:109]
	global_store_dwordx4 v[132:133], v[106:109], off offset:1024 nt
	s_nop 1
	v_pk_mul_f32 v[106:107], v[116:117], v[130:131] op_sel_hi:[1,0]
	v_pk_mul_f32 v[108:109], v[114:115], v[130:131] op_sel_hi:[1,0]
	v_pk_mul_f32 v[106:107], v[8:9], v[106:107]
	v_pk_mul_f32 v[108:109], v[10:11], v[108:109]
	global_store_dwordx4 v[132:133], v[106:109], off offset:2048 nt
	s_nop 1
	v_pk_mul_f32 v[106:107], v[120:121], v[130:131] op_sel_hi:[1,0]
	v_pk_mul_f32 v[108:109], v[118:119], v[130:131] op_sel_hi:[1,0]
	v_pk_mul_f32 v[106:107], v[12:13], v[106:107]
	v_pk_mul_f32 v[108:109], v[14:15], v[108:109]
	global_store_dwordx4 v[132:133], v[106:109], off offset:3072 nt
.LBB0_1561:
	s_or_b64 exec, exec, s[6:7]
	v_add_u32_e32 v35, s33, v35
	v_cmp_gt_i32_e32 vcc, s8, v35
	s_and_saveexec_b64 s[6:7], vcc
	s_cbranch_execz .LBB0_1563
	s_waitcnt vmcnt(31)
	v_lshlrev_b32_e32 v106, 16, v104
	v_and_b32_e32 v107, 0xffff0000, v104
	v_lshlrev_b32_e32 v104, 16, v105
	v_and_b32_e32 v105, 0xffff0000, v105
	v_lshlrev_b32_e32 v108, 16, v102
	v_and_b32_e32 v109, 0xffff0000, v102
	v_lshlrev_b32_e32 v102, 16, v103
	v_and_b32_e32 v103, 0xffff0000, v103
	v_pk_add_f32 v[102:103], v[102:103], v[104:105]
	v_pk_add_f32 v[104:105], v[108:109], v[106:107]
	s_waitcnt vmcnt(30)
	v_lshlrev_b32_e32 v106, 16, v100
	v_and_b32_e32 v107, 0xffff0000, v100
	v_lshlrev_b32_e32 v100, 16, v101
	v_and_b32_e32 v101, 0xffff0000, v101
	v_lshlrev_b32_e32 v108, 16, v98
	v_and_b32_e32 v109, 0xffff0000, v98
	v_lshlrev_b32_e32 v98, 16, v99
	v_and_b32_e32 v99, 0xffff0000, v99
	v_pk_add_f32 v[98:99], v[98:99], v[100:101]
	v_pk_add_f32 v[100:101], v[108:109], v[106:107]
	s_waitcnt vmcnt(29)
	v_lshlrev_b32_e32 v106, 16, v96
	v_and_b32_e32 v107, 0xffff0000, v96
	v_lshlrev_b32_e32 v96, 16, v97
	v_and_b32_e32 v97, 0xffff0000, v97
	v_lshlrev_b32_e32 v108, 16, v94
	v_and_b32_e32 v109, 0xffff0000, v94
	v_lshlrev_b32_e32 v94, 16, v95
	v_and_b32_e32 v95, 0xffff0000, v95
	v_pk_add_f32 v[94:95], v[94:95], v[96:97]
	v_pk_add_f32 v[96:97], v[108:109], v[106:107]
	s_waitcnt vmcnt(28)
	v_lshlrev_b32_e32 v106, 16, v92
	v_and_b32_e32 v107, 0xffff0000, v92
	v_lshlrev_b32_e32 v108, 16, v90
	v_and_b32_e32 v109, 0xffff0000, v90
	v_lshlrev_b32_e32 v92, 16, v93
	v_and_b32_e32 v93, 0xffff0000, v93
	v_lshlrev_b32_e32 v90, 16, v91
	v_and_b32_e32 v91, 0xffff0000, v91
	v_pk_add_f32 v[106:107], v[108:109], v[106:107]
	v_mov_b32_e32 v108, v105
	v_mov_b32_e32 v109, v101
	v_pk_add_f32 v[92:93], v[90:91], v[92:93]
	v_mov_b32_e32 v90, v104
	v_mov_b32_e32 v91, v100
	v_pk_mul_f32 v[108:109], v[108:109], v[108:109]
	v_mov_b32_e32 v110, v97
	v_pk_fma_f32 v[90:91], v[90:91], v[90:91], v[108:109]
	v_mov_b32_e32 v108, v102
	v_mov_b32_e32 v109, v98
	v_pk_fma_f32 v[90:91], v[108:109], v[108:109], v[90:91]
	v_mov_b32_e32 v108, v103
	v_mov_b32_e32 v109, v99
	v_mov_b32_e32 v111, v107
	v_pk_fma_f32 v[90:91], v[108:109], v[108:109], v[90:91]
	v_mov_b32_e32 v108, v96
	v_mov_b32_e32 v109, v106
	v_pk_mul_f32 v[110:111], v[110:111], v[110:111]
	v_add_f32_e32 v53, v90, v91
	v_pk_fma_f32 v[108:109], v[108:109], v[108:109], v[110:111]
	v_mov_b32_e32 v110, v94
	v_mov_b32_e32 v111, v92
	v_pk_fma_f32 v[108:109], v[110:111], v[110:111], v[108:109]
	v_mov_b32_e32 v110, v95
	v_mov_b32_e32 v111, v93
	v_pk_fma_f32 v[108:109], v[110:111], v[110:111], v[108:109]
	v_ashrrev_i32_e32 v89, 31, v88
	v_add_f32_e32 v53, v53, v108
	v_add_f32_e32 v53, v53, v109
	v_mov_b32_e32 v71, v53
	v_lshlrev_b64 v[88:89], 12, v[88:89]
	v_lshl_add_u64 v[110:111], v[20:21], 0, v[88:89]
	s_nop 1
	v_permlane32_swap_b32_e32 v71, v53
	s_nop 1
	v_add_f32_e32 v53, v53, v71
	v_mov_b32_e32 v71, v53
	s_nop 1
	v_permlane16_swap_b32_e32 v71, v53
	s_nop 1
	v_add_f32_e32 v53, v53, v71
	s_nop 1
	v_add_f32_dpp v53, v53, v53 row_ror:8 row_mask:0xf bank_mask:0xf
	s_nop 1
	v_add_f32_dpp v53, v53, v53 row_ror:4 row_mask:0xf bank_mask:0xf
	s_nop 1
	v_add_f32_dpp v53, v53, v53 quad_perm:[2,3,0,1] row_mask:0xf bank_mask:0xf
	s_nop 1
	v_add_f32_dpp v53, v53, v53 quad_perm:[1,0,3,2] row_mask:0xf bank_mask:0xf
	v_fmamk_f32 v53, v53, 0x3a800000, v31
	v_rsq_f32_e32 v53, v53
	s_nop 0
	v_mov_b32_e32 v108, v53
	v_pk_mul_f32 v[88:89], v[104:105], v[108:109] op_sel_hi:[1,0]
	v_pk_mul_f32 v[90:91], v[102:103], v[108:109] op_sel_hi:[1,0]
	v_pk_mul_f32 v[88:89], v[0:1], v[88:89]
	v_pk_mul_f32 v[90:91], v[2:3], v[90:91]
	global_store_dwordx4 v[110:111], v[88:91], off nt
	s_nop 1
	v_pk_mul_f32 v[88:89], v[100:101], v[108:109] op_sel_hi:[1,0]
	v_pk_mul_f32 v[90:91], v[98:99], v[108:109] op_sel_hi:[1,0]
	v_pk_mul_f32 v[88:89], v[4:5], v[88:89]
	v_pk_mul_f32 v[90:91], v[6:7], v[90:91]
	global_store_dwordx4 v[110:111], v[88:91], off offset:1024 nt
	s_nop 1
	v_pk_mul_f32 v[88:89], v[96:97], v[108:109] op_sel_hi:[1,0]
	v_pk_mul_f32 v[90:91], v[94:95], v[108:109] op_sel_hi:[1,0]
	v_pk_mul_f32 v[88:89], v[8:9], v[88:89]
	v_pk_mul_f32 v[90:91], v[10:11], v[90:91]
	global_store_dwordx4 v[110:111], v[88:91], off offset:2048 nt
	s_nop 1
	v_pk_mul_f32 v[88:89], v[106:107], v[108:109] op_sel_hi:[1,0]
	v_pk_mul_f32 v[90:91], v[92:93], v[108:109] op_sel_hi:[1,0]
	v_pk_mul_f32 v[88:89], v[12:13], v[88:89]
	v_pk_mul_f32 v[90:91], v[14:15], v[90:91]
	global_store_dwordx4 v[110:111], v[88:91], off offset:3072 nt
.LBB0_1563:
	s_or_b64 exec, exec, s[6:7]
	v_add_u32_e32 v35, s33, v35
	v_cmp_gt_i32_e32 vcc, s8, v35
	s_and_saveexec_b64 s[6:7], vcc
	s_cbranch_execz .LBB0_1565
	s_waitcnt vmcnt(23)
	v_lshlrev_b32_e32 v88, 16, v86
	v_and_b32_e32 v89, 0xffff0000, v86
	v_lshlrev_b32_e32 v86, 16, v87
	v_and_b32_e32 v87, 0xffff0000, v87
	v_lshlrev_b32_e32 v90, 16, v84
	v_and_b32_e32 v91, 0xffff0000, v84
	v_lshlrev_b32_e32 v84, 16, v85
	v_and_b32_e32 v85, 0xffff0000, v85
	v_pk_add_f32 v[84:85], v[84:85], v[86:87]
	v_pk_add_f32 v[86:87], v[90:91], v[88:89]
	s_waitcnt vmcnt(22)
	v_lshlrev_b32_e32 v88, 16, v82
	v_and_b32_e32 v89, 0xffff0000, v82
	v_lshlrev_b32_e32 v82, 16, v83
	v_and_b32_e32 v83, 0xffff0000, v83
	v_lshlrev_b32_e32 v90, 16, v80
	v_and_b32_e32 v91, 0xffff0000, v80
	v_lshlrev_b32_e32 v80, 16, v81
	v_and_b32_e32 v81, 0xffff0000, v81
	v_pk_add_f32 v[80:81], v[80:81], v[82:83]
	v_pk_add_f32 v[82:83], v[90:91], v[88:89]
	s_waitcnt vmcnt(21)
	v_lshlrev_b32_e32 v88, 16, v78
	v_and_b32_e32 v89, 0xffff0000, v78
	v_lshlrev_b32_e32 v78, 16, v79
	v_and_b32_e32 v79, 0xffff0000, v79
	v_lshlrev_b32_e32 v90, 16, v76
	v_and_b32_e32 v91, 0xffff0000, v76
	v_lshlrev_b32_e32 v76, 16, v77
	v_and_b32_e32 v77, 0xffff0000, v77
	v_pk_add_f32 v[76:77], v[76:77], v[78:79]
	v_pk_add_f32 v[78:79], v[90:91], v[88:89]
	s_waitcnt vmcnt(20)
	v_lshlrev_b32_e32 v88, 16, v74
	v_and_b32_e32 v89, 0xffff0000, v74
	v_lshlrev_b32_e32 v90, 16, v72
	v_and_b32_e32 v91, 0xffff0000, v72
	v_lshlrev_b32_e32 v74, 16, v75
	v_and_b32_e32 v75, 0xffff0000, v75
	v_lshlrev_b32_e32 v72, 16, v73
	v_and_b32_e32 v73, 0xffff0000, v73
	v_pk_add_f32 v[88:89], v[90:91], v[88:89]
	v_mov_b32_e32 v90, v87
	v_mov_b32_e32 v91, v83
	v_pk_add_f32 v[74:75], v[72:73], v[74:75]
	v_mov_b32_e32 v72, v86
	v_mov_b32_e32 v73, v82
	v_pk_mul_f32 v[90:91], v[90:91], v[90:91]
	v_mov_b32_e32 v92, v79
	v_pk_fma_f32 v[72:73], v[72:73], v[72:73], v[90:91]
	v_mov_b32_e32 v90, v84
	v_mov_b32_e32 v91, v80
	v_pk_fma_f32 v[72:73], v[90:91], v[90:91], v[72:73]
	v_mov_b32_e32 v90, v85
	v_mov_b32_e32 v91, v81
	v_mov_b32_e32 v93, v89
	v_pk_fma_f32 v[72:73], v[90:91], v[90:91], v[72:73]
	v_mov_b32_e32 v90, v78
	v_mov_b32_e32 v91, v88
	v_pk_mul_f32 v[92:93], v[92:93], v[92:93]
	v_add_f32_e32 v53, v72, v73
	v_pk_fma_f32 v[90:91], v[90:91], v[90:91], v[92:93]
	v_mov_b32_e32 v92, v76
	v_mov_b32_e32 v93, v74
	v_pk_fma_f32 v[90:91], v[92:93], v[92:93], v[90:91]
	v_mov_b32_e32 v92, v77
	v_mov_b32_e32 v93, v75
	v_pk_fma_f32 v[90:91], v[92:93], v[92:93], v[90:91]
	s_nop 0
	v_add_f32_e32 v53, v53, v90
	v_add_f32_e32 v53, v53, v91
	v_mov_b32_e32 v71, v53
	s_nop 1
	v_permlane32_swap_b32_e32 v71, v53
	s_nop 1
	v_add_f32_e32 v53, v53, v71
	v_mov_b32_e32 v71, v53
	s_nop 1
	v_permlane16_swap_b32_e32 v71, v53
	s_nop 1
	v_add_f32_e32 v53, v53, v71
	s_nop 1
	v_add_f32_dpp v53, v53, v53 row_ror:8 row_mask:0xf bank_mask:0xf
	s_nop 1
	v_add_f32_dpp v53, v53, v53 row_ror:4 row_mask:0xf bank_mask:0xf
	s_nop 1
	v_add_f32_dpp v53, v53, v53 quad_perm:[2,3,0,1] row_mask:0xf bank_mask:0xf
	s_nop 1
	v_add_f32_dpp v53, v53, v53 quad_perm:[1,0,3,2] row_mask:0xf bank_mask:0xf
	v_fmamk_f32 v53, v53, 0x3a800000, v31
	v_rsq_f32_e32 v53, v53
	v_ashrrev_i32_e32 v71, 31, v70
	v_lshlrev_b64 v[70:71], 12, v[70:71]
	v_lshl_add_u64 v[92:93], v[20:21], 0, v[70:71]
	v_mov_b32_e32 v90, v53
	v_pk_mul_f32 v[70:71], v[86:87], v[90:91] op_sel_hi:[1,0]
	v_pk_mul_f32 v[72:73], v[84:85], v[90:91] op_sel_hi:[1,0]
	v_pk_mul_f32 v[70:71], v[0:1], v[70:71]
	v_pk_mul_f32 v[72:73], v[2:3], v[72:73]
	global_store_dwordx4 v[92:93], v[70:73], off nt
	s_nop 1
	v_pk_mul_f32 v[70:71], v[82:83], v[90:91] op_sel_hi:[1,0]
	v_pk_mul_f32 v[72:73], v[80:81], v[90:91] op_sel_hi:[1,0]
	v_pk_mul_f32 v[70:71], v[4:5], v[70:71]
	v_pk_mul_f32 v[72:73], v[6:7], v[72:73]
	global_store_dwordx4 v[92:93], v[70:73], off offset:1024 nt
	s_nop 1
	v_pk_mul_f32 v[70:71], v[78:79], v[90:91] op_sel_hi:[1,0]
	v_pk_mul_f32 v[72:73], v[76:77], v[90:91] op_sel_hi:[1,0]
	v_pk_mul_f32 v[70:71], v[8:9], v[70:71]
	v_pk_mul_f32 v[72:73], v[10:11], v[72:73]
	global_store_dwordx4 v[92:93], v[70:73], off offset:2048 nt
	s_nop 1
	v_pk_mul_f32 v[70:71], v[88:89], v[90:91] op_sel_hi:[1,0]
	v_pk_mul_f32 v[72:73], v[74:75], v[90:91] op_sel_hi:[1,0]
	v_pk_mul_f32 v[70:71], v[12:13], v[70:71]
	v_pk_mul_f32 v[72:73], v[14:15], v[72:73]
	global_store_dwordx4 v[92:93], v[70:73], off offset:3072 nt
.LBB0_1565:
	s_or_b64 exec, exec, s[6:7]
	v_add_u32_e32 v35, s33, v35
	v_cmp_gt_i32_e32 vcc, s8, v35
	s_and_saveexec_b64 s[6:7], vcc
	s_cbranch_execz .LBB0_1567
	s_waitcnt vmcnt(15)
	v_lshlrev_b32_e32 v70, 16, v68
	v_and_b32_e32 v71, 0xffff0000, v68
	v_lshlrev_b32_e32 v68, 16, v69
	v_and_b32_e32 v69, 0xffff0000, v69
	v_lshlrev_b32_e32 v72, 16, v66
	v_and_b32_e32 v73, 0xffff0000, v66
	v_lshlrev_b32_e32 v66, 16, v67
	v_and_b32_e32 v67, 0xffff0000, v67
	v_pk_add_f32 v[66:67], v[66:67], v[68:69]
	v_pk_add_f32 v[68:69], v[72:73], v[70:71]
	s_waitcnt vmcnt(14)
	v_lshlrev_b32_e32 v70, 16, v64
	v_and_b32_e32 v71, 0xffff0000, v64
	v_lshlrev_b32_e32 v64, 16, v65
	v_and_b32_e32 v65, 0xffff0000, v65
	v_lshlrev_b32_e32 v72, 16, v62
	v_and_b32_e32 v73, 0xffff0000, v62
	v_lshlrev_b32_e32 v62, 16, v63
	v_and_b32_e32 v63, 0xffff0000, v63
	v_pk_add_f32 v[62:63], v[62:63], v[64:65]
	v_pk_add_f32 v[64:65], v[72:73], v[70:71]
	s_waitcnt vmcnt(13)
	v_lshlrev_b32_e32 v70, 16, v60
	v_and_b32_e32 v71, 0xffff0000, v60
	v_lshlrev_b32_e32 v60, 16, v61
	v_and_b32_e32 v61, 0xffff0000, v61
	v_lshlrev_b32_e32 v72, 16, v58
	v_and_b32_e32 v73, 0xffff0000, v58
	v_lshlrev_b32_e32 v58, 16, v59
	v_and_b32_e32 v59, 0xffff0000, v59
	v_pk_add_f32 v[58:59], v[58:59], v[60:61]
	v_pk_add_f32 v[60:61], v[72:73], v[70:71]
	s_waitcnt vmcnt(12)
	v_lshlrev_b32_e32 v70, 16, v56
	v_and_b32_e32 v71, 0xffff0000, v56
	v_lshlrev_b32_e32 v72, 16, v54
	v_and_b32_e32 v73, 0xffff0000, v54
	v_lshlrev_b32_e32 v56, 16, v57
	v_and_b32_e32 v57, 0xffff0000, v57
	v_lshlrev_b32_e32 v54, 16, v55
	v_and_b32_e32 v55, 0xffff0000, v55
	v_pk_add_f32 v[70:71], v[72:73], v[70:71]
	v_mov_b32_e32 v72, v69
	v_mov_b32_e32 v73, v65
	v_pk_add_f32 v[56:57], v[54:55], v[56:57]
	v_mov_b32_e32 v54, v68
	v_mov_b32_e32 v55, v64
	v_pk_mul_f32 v[72:73], v[72:73], v[72:73]
	v_mov_b32_e32 v74, v61
	v_pk_fma_f32 v[54:55], v[54:55], v[54:55], v[72:73]
	v_mov_b32_e32 v72, v66
	v_mov_b32_e32 v73, v62
	v_pk_fma_f32 v[54:55], v[72:73], v[72:73], v[54:55]
	v_mov_b32_e32 v72, v67
	v_mov_b32_e32 v73, v63
	v_mov_b32_e32 v75, v71
	v_pk_fma_f32 v[54:55], v[72:73], v[72:73], v[54:55]
	v_mov_b32_e32 v72, v60
	v_mov_b32_e32 v73, v70
	v_pk_mul_f32 v[74:75], v[74:75], v[74:75]
	v_add_f32_e32 v53, v54, v55
	v_pk_fma_f32 v[72:73], v[72:73], v[72:73], v[74:75]
	v_mov_b32_e32 v74, v58
	v_mov_b32_e32 v75, v56
	v_pk_fma_f32 v[72:73], v[74:75], v[74:75], v[72:73]
	v_mov_b32_e32 v74, v59
	v_mov_b32_e32 v75, v57
	v_pk_fma_f32 v[72:73], v[74:75], v[74:75], v[72:73]
	s_nop 0
	v_add_f32_e32 v53, v53, v72
	v_add_f32_e32 v53, v53, v73
	v_mov_b32_e32 v54, v53
	s_nop 1
	v_permlane32_swap_b32_e32 v54, v53
	s_nop 1
	v_add_f32_e32 v53, v53, v54
	v_mov_b32_e32 v54, v53
	s_nop 1
	v_permlane16_swap_b32_e32 v54, v53
	s_nop 1
	v_add_f32_e32 v53, v53, v54
	s_nop 1
	v_add_f32_dpp v53, v53, v53 row_ror:8 row_mask:0xf bank_mask:0xf
	s_nop 1
	v_add_f32_dpp v53, v53, v53 row_ror:4 row_mask:0xf bank_mask:0xf
	s_nop 1
	v_add_f32_dpp v53, v53, v53 quad_perm:[2,3,0,1] row_mask:0xf bank_mask:0xf
	s_nop 1
	v_add_f32_dpp v53, v53, v53 quad_perm:[1,0,3,2] row_mask:0xf bank_mask:0xf
	v_fmamk_f32 v53, v53, 0x3a800000, v31
	v_rsq_f32_e32 v54, v53
	v_ashrrev_i32_e32 v53, 31, v52
	v_lshlrev_b64 v[52:53], 12, v[52:53]
	v_lshl_add_u64 v[74:75], v[20:21], 0, v[52:53]
	v_mov_b32_e32 v72, v54
	v_pk_mul_f32 v[52:53], v[68:69], v[72:73] op_sel_hi:[1,0]
	v_pk_mul_f32 v[54:55], v[66:67], v[72:73] op_sel_hi:[1,0]
	v_pk_mul_f32 v[52:53], v[0:1], v[52:53]
	v_pk_mul_f32 v[54:55], v[2:3], v[54:55]
	global_store_dwordx4 v[74:75], v[52:55], off nt
	s_nop 1
	v_pk_mul_f32 v[52:53], v[64:65], v[72:73] op_sel_hi:[1,0]
	v_pk_mul_f32 v[54:55], v[62:63], v[72:73] op_sel_hi:[1,0]
	v_pk_mul_f32 v[52:53], v[4:5], v[52:53]
	v_pk_mul_f32 v[54:55], v[6:7], v[54:55]
	global_store_dwordx4 v[74:75], v[52:55], off offset:1024 nt
	s_nop 1
	v_pk_mul_f32 v[52:53], v[60:61], v[72:73] op_sel_hi:[1,0]
	v_pk_mul_f32 v[54:55], v[58:59], v[72:73] op_sel_hi:[1,0]
	v_pk_mul_f32 v[52:53], v[8:9], v[52:53]
	v_pk_mul_f32 v[54:55], v[10:11], v[54:55]
	global_store_dwordx4 v[74:75], v[52:55], off offset:2048 nt
	s_nop 1
	v_pk_mul_f32 v[52:53], v[70:71], v[72:73] op_sel_hi:[1,0]
	v_pk_mul_f32 v[54:55], v[56:57], v[72:73] op_sel_hi:[1,0]
	v_pk_mul_f32 v[52:53], v[12:13], v[52:53]
	v_pk_mul_f32 v[54:55], v[14:15], v[54:55]
	global_store_dwordx4 v[74:75], v[52:55], off offset:3072 nt
.LBB0_1567:
	s_or_b64 exec, exec, s[6:7]
	s_nop 0
	v_add_u32_e32 v52, s33, v35
	v_cmp_gt_i32_e32 vcc, s8, v52
	s_and_saveexec_b64 s[6:7], vcc
	s_cbranch_execz .LBB0_1558
	s_waitcnt vmcnt(7)
	v_lshlrev_b32_e32 v54, 16, v50
	v_and_b32_e32 v55, 0xffff0000, v50
	v_lshlrev_b32_e32 v50, 16, v51
	v_and_b32_e32 v51, 0xffff0000, v51
	v_lshlrev_b32_e32 v56, 16, v48
	v_and_b32_e32 v57, 0xffff0000, v48
	v_lshlrev_b32_e32 v48, 16, v49
	v_and_b32_e32 v49, 0xffff0000, v49
	v_pk_add_f32 v[48:49], v[48:49], v[50:51]
	v_pk_add_f32 v[50:51], v[56:57], v[54:55]
	s_waitcnt vmcnt(6)
	v_lshlrev_b32_e32 v54, 16, v46
	v_and_b32_e32 v55, 0xffff0000, v46
	v_lshlrev_b32_e32 v46, 16, v47
	v_and_b32_e32 v47, 0xffff0000, v47
	v_lshlrev_b32_e32 v56, 16, v44
	v_and_b32_e32 v57, 0xffff0000, v44
	v_lshlrev_b32_e32 v44, 16, v45
	v_and_b32_e32 v45, 0xffff0000, v45
	v_pk_add_f32 v[44:45], v[44:45], v[46:47]
	v_pk_add_f32 v[46:47], v[56:57], v[54:55]
	s_waitcnt vmcnt(5)
	v_lshlrev_b32_e32 v54, 16, v42
	v_and_b32_e32 v55, 0xffff0000, v42
	v_lshlrev_b32_e32 v42, 16, v43
	v_and_b32_e32 v43, 0xffff0000, v43
	v_lshlrev_b32_e32 v56, 16, v40
	v_and_b32_e32 v57, 0xffff0000, v40
	v_lshlrev_b32_e32 v40, 16, v41
	v_and_b32_e32 v41, 0xffff0000, v41
	v_pk_add_f32 v[40:41], v[40:41], v[42:43]
	v_pk_add_f32 v[42:43], v[56:57], v[54:55]
	s_waitcnt vmcnt(4)
	v_lshlrev_b32_e32 v54, 16, v38
	v_and_b32_e32 v55, 0xffff0000, v38
	v_lshlrev_b32_e32 v56, 16, v36
	v_and_b32_e32 v57, 0xffff0000, v36
	v_lshlrev_b32_e32 v38, 16, v39
	v_and_b32_e32 v39, 0xffff0000, v39
	v_lshlrev_b32_e32 v36, 16, v37
	v_and_b32_e32 v37, 0xffff0000, v37
	v_pk_add_f32 v[54:55], v[56:57], v[54:55]
	v_mov_b32_e32 v56, v51
	v_mov_b32_e32 v57, v47
	v_pk_add_f32 v[38:39], v[36:37], v[38:39]
	v_mov_b32_e32 v36, v50
	v_mov_b32_e32 v37, v46
	v_pk_mul_f32 v[56:57], v[56:57], v[56:57]
	v_mov_b32_e32 v58, v43
	v_pk_fma_f32 v[36:37], v[36:37], v[36:37], v[56:57]
	v_mov_b32_e32 v56, v48
	v_mov_b32_e32 v57, v44
	v_pk_fma_f32 v[36:37], v[56:57], v[56:57], v[36:37]
	v_mov_b32_e32 v56, v49
	v_mov_b32_e32 v57, v45
	v_mov_b32_e32 v59, v55
	v_pk_fma_f32 v[36:37], v[56:57], v[56:57], v[36:37]
	v_mov_b32_e32 v56, v42
	v_mov_b32_e32 v57, v54
	v_pk_mul_f32 v[58:59], v[58:59], v[58:59]
	v_add_f32_e32 v35, v36, v37
	v_pk_fma_f32 v[56:57], v[56:57], v[56:57], v[58:59]
	v_mov_b32_e32 v58, v40
	v_mov_b32_e32 v59, v38
	v_pk_fma_f32 v[56:57], v[58:59], v[58:59], v[56:57]
	v_mov_b32_e32 v58, v41
	v_mov_b32_e32 v59, v39
	v_pk_fma_f32 v[56:57], v[58:59], v[58:59], v[56:57]
	s_nop 0
	v_add_f32_e32 v35, v35, v56
	v_add_f32_e32 v35, v35, v57
	v_mov_b32_e32 v36, v35
	s_nop 1
	v_permlane32_swap_b32_e32 v36, v35
	s_nop 1
	v_add_f32_e32 v35, v35, v36
	v_mov_b32_e32 v36, v35
	s_nop 1
	v_permlane16_swap_b32_e32 v36, v35
	s_nop 1
	v_add_f32_e32 v35, v35, v36
	s_nop 1
	v_add_f32_dpp v35, v35, v35 row_ror:8 row_mask:0xf bank_mask:0xf
	s_nop 1
	v_add_f32_dpp v35, v35, v35 row_ror:4 row_mask:0xf bank_mask:0xf
	s_nop 1
	v_add_f32_dpp v35, v35, v35 quad_perm:[2,3,0,1] row_mask:0xf bank_mask:0xf
	s_nop 1
	v_add_f32_dpp v35, v35, v35 quad_perm:[1,0,3,2] row_mask:0xf bank_mask:0xf
	v_fmamk_f32 v35, v35, 0x3a800000, v31
	v_rsq_f32_e32 v36, v35
	v_ashrrev_i32_e32 v35, 31, v34
	v_lshlrev_b64 v[34:35], 12, v[34:35]
	v_lshl_add_u64 v[58:59], v[20:21], 0, v[34:35]
	v_mov_b32_e32 v56, v36
	v_pk_mul_f32 v[34:35], v[50:51], v[56:57] op_sel_hi:[1,0]
	v_pk_mul_f32 v[36:37], v[48:49], v[56:57] op_sel_hi:[1,0]
	v_pk_mul_f32 v[34:35], v[0:1], v[34:35]
	v_pk_mul_f32 v[36:37], v[2:3], v[36:37]
	global_store_dwordx4 v[58:59], v[34:37], off nt
	s_nop 1
	v_pk_mul_f32 v[34:35], v[46:47], v[56:57] op_sel_hi:[1,0]
	v_pk_mul_f32 v[36:37], v[44:45], v[56:57] op_sel_hi:[1,0]
	v_pk_mul_f32 v[34:35], v[4:5], v[34:35]
	v_pk_mul_f32 v[36:37], v[6:7], v[36:37]
	global_store_dwordx4 v[58:59], v[34:37], off offset:1024 nt
	s_nop 1
	v_pk_mul_f32 v[34:35], v[42:43], v[56:57] op_sel_hi:[1,0]
	v_pk_mul_f32 v[36:37], v[40:41], v[56:57] op_sel_hi:[1,0]
	v_pk_mul_f32 v[34:35], v[8:9], v[34:35]
	v_pk_mul_f32 v[36:37], v[10:11], v[36:37]
	global_store_dwordx4 v[58:59], v[34:37], off offset:2048 nt
	s_nop 1
	v_pk_mul_f32 v[34:35], v[54:55], v[56:57] op_sel_hi:[1,0]
	v_pk_mul_f32 v[36:37], v[38:39], v[56:57] op_sel_hi:[1,0]
	v_pk_mul_f32 v[34:35], v[12:13], v[34:35]
	v_pk_mul_f32 v[36:37], v[14:15], v[36:37]
	global_store_dwordx4 v[58:59], v[34:37], off offset:3072 nt
	s_branch .LBB0_1558
